# loop-edge edit: GEMM loop-head pointer-select SALU moved into phase-1 MFMA block, loop-carried increments moved into phase-4 MFMA block (on top of v7)
# speedup vs baseline: 1.0071x; 1.0018x over previous
; #define PG8_STAGE(bufoff, gbase, voff) do { _Pragma("unroll") for (int _i = 0; _i < 2; ++_i) { \
;         const unsigned m0v_ = (unsigned)(uintptr_t)(lds + (bufoff) + ldsw + _i * 8192); \
;         asm volatile("s_mov_b32 m0, %0\n\ts_nop 0\n\tglobal_load_lds_dwordx4 %1, %2\n\ts_nop 1" :: "s"(m0v_), "v"((voff)[_i]), "s"((const char*)(gbase)) : "m0", "memory"); } } while (0)
; #define PG8_LDA(dst, b, h) do { _Pragma("unroll") for (int m = 0; m < 4; ++m) _Pragma("unroll") for (int k = 0; k < 2; ++k) dst[m][k] = *(const LAS bf16x8*)(lds + PG8_SA(b, h) + aoff + m * 2048 + k * 1024); } while (0)
; #define PG8_LDB(dst, b, h) do { _Pragma("unroll") for (int n = 0; n < 2; ++n) _Pragma("unroll") for (int k = 0; k < 2; ++k) dst[n][k] = *(const LAS bf16x8*)(lds + PG8_SB(b, h) + boff + n * 2048 + k * 1024); } while (0)
; #define PG8_MMA(ai, bj, At, Bt) do { _Pragma("unroll") for (int m = 0; m < 4; ++m) _Pragma("unroll") for (int n = 0; n < 2; ++n) _Pragma("unroll") for (int k = 0; k < 2; ++k) \
;         acc[ai][bj][m][n] = __builtin_amdgcn_mfma_f32_16x16x32_bf16(Bt[n][k], At[m][k], acc[ai][bj][m][n], 0, 0, 0); } while (0)
; template <class Prob, class Epi, class Sched>
; __device__ __forceinline__ void gemm_phase(LAS unsigned char* lds, const Prob& P, const Sched& S, const Epi& E) {
;     ...
;         for (int t = 0; t < nt; t += 2) {
;             const bool last = (t == nt - 2);
;             if (Epi::MID_T >= 0) { if (t == Epi::MID_T) E.mid(acc, cur, slot, wr, wc, fr, fq, lds); }
;             const char* a1 = cA + (size_t)(t + 1) * kstep;
;             const char* a2 = last ? nA : cA + (size_t)(t + 2) * kstep; const char* b2 = last ? nB : cB + (size_t)(t + 2) * kstep;
;             const char* a3 = a2 + kstep; const char* b3 = b2 + kstep;
;             PG8_LDB(B0, 0, 0); PG8_LDB(B1, 0, 1); PG8_SCHED; PG8_LDA(At, 0, 0); PG8_STAGE(PG8_SA(1, 1), a1 + hstepA, voffA);
;             PG8_WAIT_V(8); PG8_WAIT_L(0); PG8_BAR; __builtin_amdgcn_s_setprio(1); PG8_MMA(0, 0, At, B0); PG8_MMA(0, 1, At, B1); __builtin_amdgcn_s_setprio(0); PG8_BAR; PG8_SCHED;
;             PG8_LDA(At, 0, 1); PG8_STAGE(PG8_SB(0, 0), b2, voffB); PG8_STAGE(PG8_SB(0, 1), b2 + hstepB, voffB); PG8_STAGE(PG8_SA(0, 0), a2, voffA);
;             PG8_WAIT_V(8); PG8_WAIT_L(0); PG8_BAR; __builtin_amdgcn_s_setprio(1); PG8_MMA(1, 0, At, B0); PG8_MMA(1, 1, At, B1); __builtin_amdgcn_s_setprio(0); PG8_BAR; PG8_SCHED;
.LBB0_270:
	ds_read_b128 v[136:139], v163
	ds_read_b128 v[140:143], v163 offset:1024
	ds_read_b128 v[144:147], v163 offset:2048
	ds_read_b128 v[148:151], v163 offset:3072
	s_waitcnt vmcnt(0)
	ds_read_b128 v[152:155], v164
	ds_read_b128 v[156:159], v164 offset:1024
	ds_read_b128 v[170:173], v164 offset:2048
	ds_read_b128 v[174:177], v164 offset:3072
	ds_read_b128 v[178:181], v165
	ds_read_b128 v[182:185], v165 offset:1024
	ds_read_b128 v[186:189], v165 offset:2048
	ds_read_b128 v[190:193], v165 offset:3072
	ds_read_b128 v[194:197], v165 offset:4096
	ds_read_b128 v[198:201], v165 offset:5120
	ds_read_b128 v[202:205], v165 offset:6144
	ds_read_b128 v[206:209], v165 offset:7168
	s_sub_u32 s98, s4, 0x80000
	s_subb_u32 s99, s5, 0
	s_mov_b32 m0, s72
	s_nop 0
	global_load_lds_dwordx4 v1, s[98:99]
	s_nop 1
	s_nop 0
	s_mov_b32 m0, s73
	s_nop 0
	global_load_lds_dwordx4 v161, s[98:99]
	s_nop 1
	s_mov_b32 m0, s76
	s_nop 0
	global_load_lds_dwordx4 v1, s[4:5]
	s_nop 1
	s_nop 0
	s_mov_b32 m0, s77
	s_nop 0
	global_load_lds_dwordx4 v161, s[4:5]
	s_nop 1
	s_waitcnt vmcnt(8)
	s_waitcnt lgkmcnt(0)
	s_setprio 1
	s_barrier
	v_mfma_f32_16x16x32_bf16 v[126:129], v[136:139], v[178:181], v[126:129]
	v_mfma_f32_16x16x32_bf16 v[122:125], v[144:147], v[178:181], v[122:125]
	s_cmp_eq_u32 s71, 28
	v_mfma_f32_16x16x32_bf16 v[110:113], v[136:139], v[186:189], v[110:113]
	s_cselect_b32 s68, s46, s15
	v_mfma_f32_16x16x32_bf16 v[106:109], v[144:147], v[186:189], v[106:109]
	s_cselect_b32 s69, s47, s43
	v_mfma_f32_16x16x32_bf16 v[94:97], v[136:139], v[194:197], v[94:97]
	s_cselect_b32 s54, s48, s45
	v_mfma_f32_16x16x32_bf16 v[90:93], v[144:147], v[194:197], v[90:93]
	s_cselect_b32 s55, s49, s70
	v_mfma_f32_16x16x32_bf16 v[78:81], v[136:139], v[202:205], v[78:81]
	s_add_u32 s6, s68, 0x80
	v_mfma_f32_16x16x32_bf16 v[74:77], v[144:147], v[202:205], v[74:77]
	s_addc_u32 s7, s69, 0
	v_mfma_f32_16x16x32_bf16 v[118:121], v[152:155], v[178:181], v[118:121]
	v_mfma_f32_16x16x32_bf16 v[114:117], v[170:173], v[178:181], v[114:117]
	v_mfma_f32_16x16x32_bf16 v[102:105], v[152:155], v[186:189], v[102:105]
	v_mfma_f32_16x16x32_bf16 v[98:101], v[170:173], v[186:189], v[98:101]
	v_mfma_f32_16x16x32_bf16 v[86:89], v[152:155], v[194:197], v[86:89]
	v_mfma_f32_16x16x32_bf16 v[82:85], v[170:173], v[194:197], v[82:85]
	v_mfma_f32_16x16x32_bf16 v[70:73], v[152:155], v[202:205], v[70:73]
	v_mfma_f32_16x16x32_bf16 v[66:69], v[170:173], v[202:205], v[66:69]
	v_mfma_f32_16x16x32_bf16 v[126:129], v[140:143], v[182:185], v[126:129]
	v_mfma_f32_16x16x32_bf16 v[122:125], v[148:151], v[182:185], v[122:125]
	v_mfma_f32_16x16x32_bf16 v[110:113], v[140:143], v[190:193], v[110:113]
	v_mfma_f32_16x16x32_bf16 v[106:109], v[148:151], v[190:193], v[106:109]
	v_mfma_f32_16x16x32_bf16 v[94:97], v[140:143], v[198:201], v[94:97]
	v_mfma_f32_16x16x32_bf16 v[90:93], v[148:151], v[198:201], v[90:93]
	v_mfma_f32_16x16x32_bf16 v[78:81], v[140:143], v[206:209], v[78:81]
	v_mfma_f32_16x16x32_bf16 v[74:77], v[148:151], v[206:209], v[74:77]
	v_mfma_f32_16x16x32_bf16 v[118:121], v[156:159], v[182:185], v[118:121]
	v_mfma_f32_16x16x32_bf16 v[114:117], v[174:177], v[182:185], v[114:117]
	v_mfma_f32_16x16x32_bf16 v[102:105], v[156:159], v[190:193], v[102:105]
	v_mfma_f32_16x16x32_bf16 v[98:101], v[174:177], v[190:193], v[98:101]
	v_mfma_f32_16x16x32_bf16 v[86:89], v[156:159], v[198:201], v[86:89]
	v_mfma_f32_16x16x32_bf16 v[82:85], v[174:177], v[198:201], v[82:85]
	v_mfma_f32_16x16x32_bf16 v[70:73], v[156:159], v[206:209], v[70:73]
	v_mfma_f32_16x16x32_bf16 v[66:69], v[174:177], v[206:209], v[66:69]
	s_barrier
	s_setprio 0
	ds_read_b128 v[178:181], v165 offset:16384
	ds_read_b128 v[182:185], v165 offset:17408
	ds_read_b128 v[186:189], v165 offset:18432
	ds_read_b128 v[190:193], v165 offset:19456
	ds_read_b128 v[194:197], v165 offset:20480
	ds_read_b128 v[198:201], v165 offset:21504
	ds_read_b128 v[202:205], v165 offset:22528
	ds_read_b128 v[206:209], v165 offset:23552
	s_mov_b32 m0, s34
	s_nop 0
	global_load_lds_dwordx4 v160, s[54:55]
	s_nop 1
	s_add_u32 s82, s54, 0x80000
	s_mov_b32 m0, s35
	s_nop 0
	global_load_lds_dwordx4 v162, s[54:55]
	s_nop 1
	s_addc_u32 s83, s55, 0
	s_mov_b32 m0, s53
	s_nop 0
	global_load_lds_dwordx4 v160, s[82:83]
	s_nop 1
	s_nop 0
	s_mov_b32 m0, s56
	s_nop 0
	global_load_lds_dwordx4 v162, s[82:83]
	s_nop 1
	s_nop 0
	s_waitcnt vmcnt(6)
	s_waitcnt lgkmcnt(0)
	s_setprio 1
	s_barrier
	v_mfma_f32_16x16x32_bf16 v[62:65], v[136:139], v[178:181], v[62:65]
	v_mfma_f32_16x16x32_bf16 v[58:61], v[144:147], v[178:181], v[58:61]
	v_mfma_f32_16x16x32_bf16 v[46:49], v[136:139], v[186:189], v[46:49]
	v_mfma_f32_16x16x32_bf16 v[42:45], v[144:147], v[186:189], v[42:45]
	v_mfma_f32_16x16x32_bf16 v[30:33], v[136:139], v[194:197], v[30:33]
	v_mfma_f32_16x16x32_bf16 v[26:29], v[144:147], v[194:197], v[26:29]
	v_mfma_f32_16x16x32_bf16 v[14:17], v[136:139], v[202:205], v[14:17]
	v_mfma_f32_16x16x32_bf16 v[10:13], v[144:147], v[202:205], v[10:13]
	v_mfma_f32_16x16x32_bf16 v[54:57], v[152:155], v[178:181], v[54:57]
	v_mfma_f32_16x16x32_bf16 v[50:53], v[170:173], v[178:181], v[50:53]
	v_mfma_f32_16x16x32_bf16 v[38:41], v[152:155], v[186:189], v[38:41]
	v_mfma_f32_16x16x32_bf16 v[34:37], v[170:173], v[186:189], v[34:37]
	v_mfma_f32_16x16x32_bf16 v[22:25], v[152:155], v[194:197], v[22:25]
	v_mfma_f32_16x16x32_bf16 v[18:21], v[170:173], v[194:197], v[18:21]
	v_mfma_f32_16x16x32_bf16 v[6:9], v[152:155], v[202:205], v[6:9]
	v_mfma_f32_16x16x32_bf16 v[2:5], v[170:173], v[202:205], v[2:5]
	v_mfma_f32_16x16x32_bf16 v[62:65], v[140:143], v[182:185], v[62:65]
	v_mfma_f32_16x16x32_bf16 v[58:61], v[148:151], v[182:185], v[58:61]
	v_mfma_f32_16x16x32_bf16 v[46:49], v[140:143], v[190:193], v[46:49]
	v_mfma_f32_16x16x32_bf16 v[42:45], v[148:151], v[190:193], v[42:45]
	v_mfma_f32_16x16x32_bf16 v[30:33], v[140:143], v[198:201], v[30:33]
	v_mfma_f32_16x16x32_bf16 v[26:29], v[148:151], v[198:201], v[26:29]
	v_mfma_f32_16x16x32_bf16 v[14:17], v[140:143], v[206:209], v[14:17]
	v_mfma_f32_16x16x32_bf16 v[10:13], v[148:151], v[206:209], v[10:13]
	v_mfma_f32_16x16x32_bf16 v[54:57], v[156:159], v[182:185], v[54:57]
	v_mfma_f32_16x16x32_bf16 v[50:53], v[174:177], v[182:185], v[50:53]
	v_mfma_f32_16x16x32_bf16 v[38:41], v[156:159], v[190:193], v[38:41]
	v_mfma_f32_16x16x32_bf16 v[34:37], v[174:177], v[190:193], v[34:37]
	v_mfma_f32_16x16x32_bf16 v[22:25], v[156:159], v[198:201], v[22:25]
	v_mfma_f32_16x16x32_bf16 v[18:21], v[174:177], v[198:201], v[18:21]
	v_mfma_f32_16x16x32_bf16 v[6:9], v[156:159], v[206:209], v[6:9]
	v_mfma_f32_16x16x32_bf16 v[2:5], v[174:177], v[206:209], v[2:5]
	s_barrier
; #define PG8_STAGE(bufoff, gbase, voff) do { _Pragma("unroll") for (int _i = 0; _i < 2; ++_i) { \
;         const unsigned m0v_ = (unsigned)(uintptr_t)(lds + (bufoff) + ldsw + _i * 8192); \
;         asm volatile("s_mov_b32 m0, %0\n\ts_nop 0\n\tglobal_load_lds_dwordx4 %1, %2\n\ts_nop 1" :: "s"(m0v_), "v"((voff)[_i]), "s"((const char*)(gbase)) : "m0", "memory"); } } while (0)
; #define PG8_LDA(dst, b, h) do { _Pragma("unroll") for (int m = 0; m < 4; ++m) _Pragma("unroll") for (int k = 0; k < 2; ++k) dst[m][k] = *(const LAS bf16x8*)(lds + PG8_SA(b, h) + aoff + m * 2048 + k * 1024); } while (0)
; #define PG8_LDB(dst, b, h) do { _Pragma("unroll") for (int n = 0; n < 2; ++n) _Pragma("unroll") for (int k = 0; k < 2; ++k) dst[n][k] = *(const LAS bf16x8*)(lds + PG8_SB(b, h) + boff + n * 2048 + k * 1024); } while (0)
; #define PG8_MMA(ai, bj, At, Bt) do { _Pragma("unroll") for (int m = 0; m < 4; ++m) _Pragma("unroll") for (int n = 0; n < 2; ++n) _Pragma("unroll") for (int k = 0; k < 2; ++k) \
;         acc[ai][bj][m][n] = __builtin_amdgcn_mfma_f32_16x16x32_bf16(Bt[n][k], At[m][k], acc[ai][bj][m][n], 0, 0, 0); } while (0)
; #define PG8_WAIT_V(n) asm volatile("s_waitcnt vmcnt(" #n ")" ::: "memory")
; #define PG8_WAIT_L(n) asm volatile("s_waitcnt lgkmcnt(" #n ")" ::: "memory")
; #define PG8_BAR __builtin_amdgcn_s_barrier()
; #define PG8_SCHED __builtin_amdgcn_sched_barrier(0)
; template <class Prob, class Epi, class Sched>
; __device__ __forceinline__ void gemm_phase(LAS unsigned char* lds, const Prob& P, const Sched& S, const Epi& E) {
;     ...
;             PG8_LDB(B0, 1, 0); PG8_LDB(B1, 1, 1); PG8_SCHED; PG8_LDA(At, 1, 0); PG8_STAGE(PG8_SA(0, 1), a2 + hstepA, voffA);
;             PG8_WAIT_V(8); PG8_WAIT_L(0); PG8_BAR; __builtin_amdgcn_s_setprio(1); PG8_MMA(0, 0, At, B0); PG8_MMA(0, 1, At, B1); __builtin_amdgcn_s_setprio(0); PG8_BAR; PG8_SCHED;
;             PG8_LDA(At, 1, 1); PG8_STAGE(PG8_SB(1, 0), b3, voffB); PG8_STAGE(PG8_SB(1, 1), b3 + hstepB, voffB); PG8_STAGE(PG8_SA(1, 0), a3, voffA);
;             PG8_WAIT_V(8); PG8_WAIT_L(0); PG8_BAR; __builtin_amdgcn_s_setprio(1); PG8_MMA(1, 0, At, B0); PG8_MMA(1, 1, At, B1); __builtin_amdgcn_s_setprio(0); PG8_BAR; PG8_SCHED;
;         }
	s_setprio 0
	ds_read_b128 v[136:139], v166
	ds_read_b128 v[140:143], v166 offset:1024
	ds_read_b128 v[144:147], v166 offset:2048
	ds_read_b128 v[148:151], v166 offset:3072
	ds_read_b128 v[152:155], v167
	ds_read_b128 v[156:159], v167 offset:1024
	ds_read_b128 v[170:173], v167 offset:2048
	ds_read_b128 v[174:177], v167 offset:3072
	ds_read_b128 v[178:181], v165 offset:32768
	ds_read_b128 v[182:185], v165 offset:33792
	ds_read_b128 v[186:189], v165 offset:34816
	ds_read_b128 v[190:193], v165 offset:35840
	ds_read_b128 v[194:197], v165 offset:36864
	ds_read_b128 v[198:201], v165 offset:37888
	ds_read_b128 v[202:205], v165 offset:38912
	ds_read_b128 v[206:209], v165 offset:39936
	s_mov_b32 m0, s3
	s_nop 0
	global_load_lds_dwordx4 v1, s[68:69]
	s_nop 1
	s_nop 0
	s_mov_b32 m0, s57
	s_nop 0
	global_load_lds_dwordx4 v161, s[68:69]
	s_nop 1
	s_add_u32 s68, s68, 0x80000
	s_addc_u32 s69, s69, 0
	s_mov_b32 m0, s58
	s_nop 0
	global_load_lds_dwordx4 v1, s[68:69]
	s_nop 1
	s_nop 0
	s_mov_b32 m0, s59
	s_nop 0
	global_load_lds_dwordx4 v161, s[68:69]
	s_nop 1
	s_waitcnt vmcnt(8)
	s_waitcnt lgkmcnt(0)
	s_setprio 1
	s_barrier
	v_mfma_f32_16x16x32_bf16 v[126:129], v[136:139], v[178:181], v[126:129]
	v_mfma_f32_16x16x32_bf16 v[122:125], v[144:147], v[178:181], v[122:125]
	v_mfma_f32_16x16x32_bf16 v[110:113], v[136:139], v[186:189], v[110:113]
	v_mfma_f32_16x16x32_bf16 v[106:109], v[144:147], v[186:189], v[106:109]
	v_mfma_f32_16x16x32_bf16 v[94:97], v[136:139], v[194:197], v[94:97]
	v_mfma_f32_16x16x32_bf16 v[90:93], v[144:147], v[194:197], v[90:93]
	v_mfma_f32_16x16x32_bf16 v[78:81], v[136:139], v[202:205], v[78:81]
	v_mfma_f32_16x16x32_bf16 v[74:77], v[144:147], v[202:205], v[74:77]
	v_mfma_f32_16x16x32_bf16 v[118:121], v[152:155], v[178:181], v[118:121]
	v_mfma_f32_16x16x32_bf16 v[114:117], v[170:173], v[178:181], v[114:117]
	v_mfma_f32_16x16x32_bf16 v[102:105], v[152:155], v[186:189], v[102:105]
	v_mfma_f32_16x16x32_bf16 v[98:101], v[170:173], v[186:189], v[98:101]
	v_mfma_f32_16x16x32_bf16 v[86:89], v[152:155], v[194:197], v[86:89]
	v_mfma_f32_16x16x32_bf16 v[82:85], v[170:173], v[194:197], v[82:85]
	v_mfma_f32_16x16x32_bf16 v[70:73], v[152:155], v[202:205], v[70:73]
	v_mfma_f32_16x16x32_bf16 v[66:69], v[170:173], v[202:205], v[66:69]
	v_mfma_f32_16x16x32_bf16 v[126:129], v[140:143], v[182:185], v[126:129]
	v_mfma_f32_16x16x32_bf16 v[122:125], v[148:151], v[182:185], v[122:125]
	v_mfma_f32_16x16x32_bf16 v[110:113], v[140:143], v[190:193], v[110:113]
	v_mfma_f32_16x16x32_bf16 v[106:109], v[148:151], v[190:193], v[106:109]
	v_mfma_f32_16x16x32_bf16 v[94:97], v[140:143], v[198:201], v[94:97]
	v_mfma_f32_16x16x32_bf16 v[90:93], v[148:151], v[198:201], v[90:93]
	v_mfma_f32_16x16x32_bf16 v[78:81], v[140:143], v[206:209], v[78:81]
	v_mfma_f32_16x16x32_bf16 v[74:77], v[148:151], v[206:209], v[74:77]
	v_mfma_f32_16x16x32_bf16 v[118:121], v[156:159], v[182:185], v[118:121]
	v_mfma_f32_16x16x32_bf16 v[114:117], v[174:177], v[182:185], v[114:117]
	v_mfma_f32_16x16x32_bf16 v[102:105], v[156:159], v[190:193], v[102:105]
	v_mfma_f32_16x16x32_bf16 v[98:101], v[174:177], v[190:193], v[98:101]
	v_mfma_f32_16x16x32_bf16 v[86:89], v[156:159], v[198:201], v[86:89]
	v_mfma_f32_16x16x32_bf16 v[82:85], v[174:177], v[198:201], v[82:85]
	v_mfma_f32_16x16x32_bf16 v[70:73], v[156:159], v[206:209], v[70:73]
	v_mfma_f32_16x16x32_bf16 v[66:69], v[174:177], v[206:209], v[66:69]
	s_barrier
	s_setprio 0
	ds_read_b128 v[178:181], v165 offset:49152
	ds_read_b128 v[182:185], v165 offset:50176
	ds_read_b128 v[186:189], v165 offset:51200
	ds_read_b128 v[190:193], v165 offset:52224
	ds_read_b128 v[194:197], v165 offset:53248
	ds_read_b128 v[198:201], v165 offset:54272
	ds_read_b128 v[202:205], v165 offset:55296
	ds_read_b128 v[206:209], v165 offset:56320
	s_add_u32 s68, s54, 0x80
	s_addc_u32 s69, s55, 0
	s_mov_b32 m0, s64
	s_nop 0
	global_load_lds_dwordx4 v160, s[68:69]
	s_nop 1
	s_add_u32 s54, s54, 0x80080
	s_mov_b32 m0, s65
	s_nop 0
	global_load_lds_dwordx4 v162, s[68:69]
	s_nop 1
	s_addc_u32 s55, s55, 0
	s_mov_b32 m0, s74
	s_nop 0
	global_load_lds_dwordx4 v160, s[54:55]
	s_nop 1
	s_nop 0
	s_mov_b32 m0, s75
	s_nop 0
	global_load_lds_dwordx4 v162, s[54:55]
	s_nop 1
	s_nop 0
	s_waitcnt vmcnt(6)
	s_waitcnt lgkmcnt(0)
	s_setprio 1
	s_barrier
	v_mfma_f32_16x16x32_bf16 v[62:65], v[136:139], v[178:181], v[62:65]
	v_mfma_f32_16x16x32_bf16 v[58:61], v[144:147], v[178:181], v[58:61]
	s_add_i32 s71, s71, 2
	v_mfma_f32_16x16x32_bf16 v[46:49], v[136:139], v[186:189], v[46:49]
	s_add_u32 s15, s15, 0x100
	v_mfma_f32_16x16x32_bf16 v[42:45], v[144:147], v[186:189], v[42:45]
	s_addc_u32 s43, s43, 0
	v_mfma_f32_16x16x32_bf16 v[30:33], v[136:139], v[194:197], v[30:33]
	s_add_u32 s45, s45, 0x100
	v_mfma_f32_16x16x32_bf16 v[26:29], v[144:147], v[194:197], v[26:29]
	s_addc_u32 s70, s70, 0
	v_mfma_f32_16x16x32_bf16 v[14:17], v[136:139], v[202:205], v[14:17]
	s_add_u32 s4, s4, 0x100
	v_mfma_f32_16x16x32_bf16 v[10:13], v[144:147], v[202:205], v[10:13]
	s_addc_u32 s5, s5, 0
	v_mfma_f32_16x16x32_bf16 v[54:57], v[152:155], v[178:181], v[54:57]
	v_mfma_f32_16x16x32_bf16 v[50:53], v[170:173], v[178:181], v[50:53]
	v_mfma_f32_16x16x32_bf16 v[38:41], v[152:155], v[186:189], v[38:41]
	v_mfma_f32_16x16x32_bf16 v[34:37], v[170:173], v[186:189], v[34:37]
	v_mfma_f32_16x16x32_bf16 v[22:25], v[152:155], v[194:197], v[22:25]
	v_mfma_f32_16x16x32_bf16 v[18:21], v[170:173], v[194:197], v[18:21]
	v_mfma_f32_16x16x32_bf16 v[6:9], v[152:155], v[202:205], v[6:9]
	v_mfma_f32_16x16x32_bf16 v[2:5], v[170:173], v[202:205], v[2:5]
	v_mfma_f32_16x16x32_bf16 v[62:65], v[140:143], v[182:185], v[62:65]
	v_mfma_f32_16x16x32_bf16 v[58:61], v[148:151], v[182:185], v[58:61]
	v_mfma_f32_16x16x32_bf16 v[46:49], v[140:143], v[190:193], v[46:49]
	v_mfma_f32_16x16x32_bf16 v[42:45], v[148:151], v[190:193], v[42:45]
	v_mfma_f32_16x16x32_bf16 v[30:33], v[140:143], v[198:201], v[30:33]
	v_mfma_f32_16x16x32_bf16 v[26:29], v[148:151], v[198:201], v[26:29]
	v_mfma_f32_16x16x32_bf16 v[14:17], v[140:143], v[206:209], v[14:17]
	v_mfma_f32_16x16x32_bf16 v[10:13], v[148:151], v[206:209], v[10:13]
	v_mfma_f32_16x16x32_bf16 v[54:57], v[156:159], v[182:185], v[54:57]
	v_mfma_f32_16x16x32_bf16 v[50:53], v[174:177], v[182:185], v[50:53]
	v_mfma_f32_16x16x32_bf16 v[38:41], v[156:159], v[190:193], v[38:41]
	v_mfma_f32_16x16x32_bf16 v[34:37], v[174:177], v[190:193], v[34:37]
	v_mfma_f32_16x16x32_bf16 v[22:25], v[156:159], v[198:201], v[22:25]
	v_mfma_f32_16x16x32_bf16 v[18:21], v[174:177], v[198:201], v[18:21]
	v_mfma_f32_16x16x32_bf16 v[6:9], v[156:159], v[206:209], v[6:9]
	v_mfma_f32_16x16x32_bf16 v[2:5], v[174:177], v[206:209], v[2:5]
	s_barrier
	s_setprio 0
	s_cmp_gt_u32 s71, 29
	s_cbranch_scc0 .LBB0_270
	s_and_b64 vcc, exec, s[40:41]
	s_cbranch_vccz .LBB0_273
	s_barrier

; #define PG8_STAGE(bufoff, gbase, voff) do { _Pragma("unroll") for (int _i = 0; _i < 2; ++_i) { \
;         const unsigned m0v_ = (unsigned)(uintptr_t)(lds + (bufoff) + ldsw + _i * 8192); \
;         asm volatile("s_mov_b32 m0, %0\n\ts_nop 0\n\tglobal_load_lds_dwordx4 %1, %2\n\ts_nop 1" :: "s"(m0v_), "v"((voff)[_i]), "s"((const char*)(gbase)) : "m0", "memory"); } } while (0)
; #define PG8_LDA(dst, b, h) do { _Pragma("unroll") for (int m = 0; m < 4; ++m) _Pragma("unroll") for (int k = 0; k < 2; ++k) dst[m][k] = *(const LAS bf16x8*)(lds + PG8_SA(b, h) + aoff + m * 2048 + k * 1024); } while (0)
; #define PG8_LDB(dst, b, h) do { _Pragma("unroll") for (int n = 0; n < 2; ++n) _Pragma("unroll") for (int k = 0; k < 2; ++k) dst[n][k] = *(const LAS bf16x8*)(lds + PG8_SB(b, h) + boff + n * 2048 + k * 1024); } while (0)
; #define PG8_MMA(ai, bj, At, Bt) do { _Pragma("unroll") for (int m = 0; m < 4; ++m) _Pragma("unroll") for (int n = 0; n < 2; ++n) _Pragma("unroll") for (int k = 0; k < 2; ++k) \
;         acc[ai][bj][m][n] = __builtin_amdgcn_mfma_f32_16x16x32_bf16(Bt[n][k], At[m][k], acc[ai][bj][m][n], 0, 0, 0); } while (0)
; #define PG8_WAIT_V(n) asm volatile("s_waitcnt vmcnt(" #n ")" ::: "memory")
; #define PG8_WAIT_L(n) asm volatile("s_waitcnt lgkmcnt(" #n ")" ::: "memory")
; template <class Prob, class Epi, class Sched>
; __device__ __forceinline__ void gemm_phase(LAS unsigned char* lds, const Prob& P, const Sched& S, const Epi& E) {
;     ...
;         for (int t = 0; t < nt; t += 2) {
;             const bool last = (t == nt - 2);
;             if (Epi::MID_T >= 0) { if (t == Epi::MID_T) E.mid(acc, cur, slot, wr, wc, fr, fq, lds); }
;             const char* a1 = cA + (size_t)(t + 1) * kstep;
;             const char* a2 = last ? nA : cA + (size_t)(t + 2) * kstep; const char* b2 = last ? nB : cB + (size_t)(t + 2) * kstep;
;             const char* a3 = a2 + kstep; const char* b3 = b2 + kstep;
;             PG8_LDB(B0, 0, 0); PG8_LDB(B1, 0, 1); PG8_SCHED; PG8_LDA(At, 0, 0); PG8_STAGE(PG8_SA(1, 1), a1 + hstepA, voffA);
;             PG8_WAIT_V(8); PG8_WAIT_L(0); PG8_BAR; __builtin_amdgcn_s_setprio(1); PG8_MMA(0, 0, At, B0); PG8_MMA(0, 1, At, B1); __builtin_amdgcn_s_setprio(0); PG8_BAR; PG8_SCHED;
;             PG8_LDA(At, 0, 1); PG8_STAGE(PG8_SB(0, 0), b2, voffB); PG8_STAGE(PG8_SB(0, 1), b2 + hstepB, voffB); PG8_STAGE(PG8_SA(0, 0), a2, voffA);
.LBB0_451:
	v_add_u32_e32 v130, 0x10000, v219
	ds_read_b128 v[132:135], v130
	s_waitcnt vmcnt(4)
	ds_read_b128 v[136:139], v130 offset:1024
	ds_read_b128 v[140:143], v130 offset:2048
	s_waitcnt vmcnt(3)
	ds_read_b128 v[144:147], v130 offset:3072
	v_add_u32_e32 v130, 0x14000, v219
	s_waitcnt vmcnt(2)
	ds_read_b128 v[148:151], v130
	s_waitcnt vmcnt(0)
	ds_read_b128 v[152:155], v130 offset:1024
	ds_read_b128 v[156:159], v130 offset:2048
	ds_read_b128 v[160:163], v130 offset:3072
	ds_read_b128 v[164:167], v220
	ds_read_b128 v[168:171], v220 offset:1024
	ds_read_b128 v[172:175], v220 offset:2048
	ds_read_b128 v[176:179], v220 offset:3072
	ds_read_b128 v[180:183], v220 offset:4096
	ds_read_b128 v[184:187], v220 offset:5120
	ds_read_b128 v[188:191], v220 offset:6144
	ds_read_b128 v[192:195], v220 offset:7168
	s_add_u32 s74, s49, s4
	s_addc_u32 s75, s54, s5
	s_add_u32 s74, s74, 0xffffff80
	s_addc_u32 s75, s75, -1
	s_sub_u32 s98, s74, 0x80000
	s_subb_u32 s99, s75, 0
	s_mov_b32 m0, s70
	s_nop 0
	global_load_lds_dwordx4 v1, s[98:99]
	s_nop 1
	s_nop 0
	s_mov_b32 m0, s71
	s_nop 0
	global_load_lds_dwordx4 v217, s[98:99]
	s_nop 1
	s_mov_b32 m0, s46
	s_nop 0
	global_load_lds_dwordx4 v1, s[74:75]
	s_nop 1
	s_nop 0
	s_mov_b32 m0, s47
	s_nop 0
	global_load_lds_dwordx4 v217, s[74:75]
	s_nop 1
	s_waitcnt vmcnt(8)
	s_waitcnt lgkmcnt(0)
	s_setprio 1
	s_barrier
	v_mfma_f32_16x16x32_bf16 v[2:5], v[132:135], v[164:167], v[2:5]
	v_mfma_f32_16x16x32_bf16 v[62:65], v[140:143], v[164:167], v[62:65]
	s_add_i32 s68, s6, 2
	v_mfma_f32_16x16x32_bf16 v[58:61], v[132:135], v[172:175], v[58:61]
	s_add_u32 s7, s78, s4
	v_mfma_f32_16x16x32_bf16 v[54:57], v[140:143], v[172:175], v[54:57]
	s_addc_u32 s8, s79, s5
	v_mfma_f32_16x16x32_bf16 v[50:53], v[132:135], v[180:183], v[50:53]
	s_add_u32 s9, s80, s4
	v_mfma_f32_16x16x32_bf16 v[46:49], v[140:143], v[180:183], v[46:49]
	s_addc_u32 s100, s81, s5
	v_mfma_f32_16x16x32_bf16 v[42:45], v[132:135], v[188:191], v[42:45]
	s_cmp_eq_u32 s55, s6
	v_mfma_f32_16x16x32_bf16 v[38:41], v[140:143], v[188:191], v[38:41]
	s_cselect_b32 s10, s88, s7
	v_mfma_f32_16x16x32_bf16 v[34:37], v[148:151], v[164:167], v[34:37]
	s_cselect_b32 s11, s89, s8
	v_mfma_f32_16x16x32_bf16 v[30:33], v[156:159], v[164:167], v[30:33]
	s_cselect_b32 s8, s90, s9
	v_mfma_f32_16x16x32_bf16 v[26:29], v[148:151], v[172:175], v[26:29]
	s_cselect_b32 s9, s91, s100
	v_mfma_f32_16x16x32_bf16 v[22:25], v[156:159], v[172:175], v[22:25]
	s_add_u32 s6, s10, 0x80
	v_mfma_f32_16x16x32_bf16 v[18:21], v[148:151], v[180:183], v[18:21]
	s_addc_u32 s7, s11, 0
	v_mfma_f32_16x16x32_bf16 v[14:17], v[156:159], v[180:183], v[14:17]
	v_mfma_f32_16x16x32_bf16 v[10:13], v[148:151], v[188:191], v[10:13]
	v_mfma_f32_16x16x32_bf16 v[6:9], v[156:159], v[188:191], v[6:9]
	v_mfma_f32_16x16x32_bf16 v[2:5], v[136:139], v[168:171], v[2:5]
	v_mfma_f32_16x16x32_bf16 v[62:65], v[144:147], v[168:171], v[62:65]
	v_mfma_f32_16x16x32_bf16 v[58:61], v[136:139], v[176:179], v[58:61]
	v_mfma_f32_16x16x32_bf16 v[54:57], v[144:147], v[176:179], v[54:57]
	v_mfma_f32_16x16x32_bf16 v[50:53], v[136:139], v[184:187], v[50:53]
	v_mfma_f32_16x16x32_bf16 v[46:49], v[144:147], v[184:187], v[46:49]
	v_mfma_f32_16x16x32_bf16 v[42:45], v[136:139], v[192:195], v[42:45]
	v_mfma_f32_16x16x32_bf16 v[38:41], v[144:147], v[192:195], v[38:41]
	v_mfma_f32_16x16x32_bf16 v[34:37], v[152:155], v[168:171], v[34:37]
	v_mfma_f32_16x16x32_bf16 v[30:33], v[160:163], v[168:171], v[30:33]
	v_mfma_f32_16x16x32_bf16 v[26:29], v[152:155], v[176:179], v[26:29]
	v_mfma_f32_16x16x32_bf16 v[22:25], v[160:163], v[176:179], v[22:25]
	v_mfma_f32_16x16x32_bf16 v[18:21], v[152:155], v[184:187], v[18:21]
	v_mfma_f32_16x16x32_bf16 v[14:17], v[160:163], v[184:187], v[14:17]
	v_mfma_f32_16x16x32_bf16 v[10:13], v[152:155], v[192:195], v[10:13]
	v_mfma_f32_16x16x32_bf16 v[6:9], v[160:163], v[192:195], v[6:9]
	s_barrier
	s_setprio 0
	ds_read_b128 v[164:167], v220 offset:16384
	ds_read_b128 v[168:171], v220 offset:17408
	ds_read_b128 v[172:175], v220 offset:18432
	ds_read_b128 v[176:179], v220 offset:19456
	ds_read_b128 v[180:183], v220 offset:20480
	ds_read_b128 v[184:187], v220 offset:21504
	ds_read_b128 v[188:191], v220 offset:22528
	ds_read_b128 v[192:195], v220 offset:23552
	s_mov_b32 m0, s67
	s_nop 0
	global_load_lds_dwordx4 v216, s[8:9]
	s_nop 1
	s_add_u32 s74, s8, 0x80000
	s_mov_b32 m0, s0
	s_nop 0
	global_load_lds_dwordx4 v218, s[8:9]
	s_nop 1
	s_addc_u32 s75, s9, 0
	s_mov_b32 m0, s1
	s_nop 0
	global_load_lds_dwordx4 v216, s[74:75]
	s_nop 1
	s_nop 0
	s_mov_b32 m0, s35
	s_nop 0
	global_load_lds_dwordx4 v218, s[74:75]
	s_nop 1
	s_nop 0
	s_waitcnt vmcnt(6)
	s_waitcnt lgkmcnt(0)
	s_setprio 1
	s_barrier
; #define PG8_STAGE(bufoff, gbase, voff) do { _Pragma("unroll") for (int _i = 0; _i < 2; ++_i) { \
;         const unsigned m0v_ = (unsigned)(uintptr_t)(lds + (bufoff) + ldsw + _i * 8192); \
;         asm volatile("s_mov_b32 m0, %0\n\ts_nop 0\n\tglobal_load_lds_dwordx4 %1, %2\n\ts_nop 1" :: "s"(m0v_), "v"((voff)[_i]), "s"((const char*)(gbase)) : "m0", "memory"); } } while (0)
; #define PG8_LDA(dst, b, h) do { _Pragma("unroll") for (int m = 0; m < 4; ++m) _Pragma("unroll") for (int k = 0; k < 2; ++k) dst[m][k] = *(const LAS bf16x8*)(lds + PG8_SA(b, h) + aoff + m * 2048 + k * 1024); } while (0)
; #define PG8_LDB(dst, b, h) do { _Pragma("unroll") for (int n = 0; n < 2; ++n) _Pragma("unroll") for (int k = 0; k < 2; ++k) dst[n][k] = *(const LAS bf16x8*)(lds + PG8_SB(b, h) + boff + n * 2048 + k * 1024); } while (0)
; #define PG8_MMA(ai, bj, At, Bt) do { _Pragma("unroll") for (int m = 0; m < 4; ++m) _Pragma("unroll") for (int n = 0; n < 2; ++n) _Pragma("unroll") for (int k = 0; k < 2; ++k) \
;         acc[ai][bj][m][n] = __builtin_amdgcn_mfma_f32_16x16x32_bf16(Bt[n][k], At[m][k], acc[ai][bj][m][n], 0, 0, 0); } while (0)
; #define PG8_WAIT_V(n) asm volatile("s_waitcnt vmcnt(" #n ")" ::: "memory")
; #define PG8_WAIT_L(n) asm volatile("s_waitcnt lgkmcnt(" #n ")" ::: "memory")
; #define PG8_BAR __builtin_amdgcn_s_barrier()
; #define PG8_SCHED __builtin_amdgcn_sched_barrier(0)
; template <class Prob, class Epi, class Sched>
; __device__ __forceinline__ void gemm_phase(LAS unsigned char* lds, const Prob& P, const Sched& S, const Epi& E) {
;     ...
;             PG8_WAIT_V(8); PG8_WAIT_L(0); PG8_BAR; __builtin_amdgcn_s_setprio(1); PG8_MMA(1, 0, At, B0); PG8_MMA(1, 1, At, B1); __builtin_amdgcn_s_setprio(0); PG8_BAR; PG8_SCHED;
;             PG8_LDB(B0, 1, 0); PG8_LDB(B1, 1, 1); PG8_SCHED; PG8_LDA(At, 1, 0); PG8_STAGE(PG8_SA(0, 1), a2 + hstepA, voffA);
	v_mfma_f32_16x16x32_bf16 v[126:129], v[132:135], v[164:167], v[126:129]
	v_mfma_f32_16x16x32_bf16 v[122:125], v[140:143], v[164:167], v[122:125]
	v_mfma_f32_16x16x32_bf16 v[118:121], v[132:135], v[172:175], v[118:121]
	v_mfma_f32_16x16x32_bf16 v[114:117], v[140:143], v[172:175], v[114:117]
	v_mfma_f32_16x16x32_bf16 v[110:113], v[132:135], v[180:183], v[110:113]
	v_mfma_f32_16x16x32_bf16 v[106:109], v[140:143], v[180:183], v[106:109]
	v_mfma_f32_16x16x32_bf16 v[102:105], v[132:135], v[188:191], v[102:105]
	v_mfma_f32_16x16x32_bf16 v[98:101], v[140:143], v[188:191], v[98:101]
	v_mfma_f32_16x16x32_bf16 v[94:97], v[148:151], v[164:167], v[94:97]
	v_mfma_f32_16x16x32_bf16 v[90:93], v[156:159], v[164:167], v[90:93]
	v_mfma_f32_16x16x32_bf16 v[86:89], v[148:151], v[172:175], v[86:89]
	v_mfma_f32_16x16x32_bf16 v[82:85], v[156:159], v[172:175], v[82:85]
	v_mfma_f32_16x16x32_bf16 v[78:81], v[148:151], v[180:183], v[78:81]
	v_mfma_f32_16x16x32_bf16 v[74:77], v[156:159], v[180:183], v[74:77]
	v_mfma_f32_16x16x32_bf16 v[70:73], v[148:151], v[188:191], v[70:73]
	v_mfma_f32_16x16x32_bf16 v[66:69], v[156:159], v[188:191], v[66:69]
	v_mfma_f32_16x16x32_bf16 v[126:129], v[136:139], v[168:171], v[126:129]
	v_mfma_f32_16x16x32_bf16 v[122:125], v[144:147], v[168:171], v[122:125]
	v_mfma_f32_16x16x32_bf16 v[118:121], v[136:139], v[176:179], v[118:121]
	v_mfma_f32_16x16x32_bf16 v[114:117], v[144:147], v[176:179], v[114:117]
	v_mfma_f32_16x16x32_bf16 v[110:113], v[136:139], v[184:187], v[110:113]
	v_mfma_f32_16x16x32_bf16 v[106:109], v[144:147], v[184:187], v[106:109]
	v_mfma_f32_16x16x32_bf16 v[102:105], v[136:139], v[192:195], v[102:105]
	v_mfma_f32_16x16x32_bf16 v[98:101], v[144:147], v[192:195], v[98:101]
	v_mfma_f32_16x16x32_bf16 v[94:97], v[152:155], v[168:171], v[94:97]
	v_mfma_f32_16x16x32_bf16 v[90:93], v[160:163], v[168:171], v[90:93]
	v_mfma_f32_16x16x32_bf16 v[86:89], v[152:155], v[176:179], v[86:89]
	v_mfma_f32_16x16x32_bf16 v[82:85], v[160:163], v[176:179], v[82:85]
	v_mfma_f32_16x16x32_bf16 v[78:81], v[152:155], v[184:187], v[78:81]
	v_mfma_f32_16x16x32_bf16 v[74:77], v[160:163], v[184:187], v[74:77]
	v_mfma_f32_16x16x32_bf16 v[70:73], v[152:155], v[192:195], v[70:73]
	v_mfma_f32_16x16x32_bf16 v[66:69], v[160:163], v[192:195], v[66:69]
	s_barrier
	s_setprio 0
	v_add_u32_e32 v130, 0x18000, v219
	ds_read_b128 v[132:135], v130
	ds_read_b128 v[136:139], v130 offset:1024
	ds_read_b128 v[140:143], v130 offset:2048
	ds_read_b128 v[144:147], v130 offset:3072
	v_add_u32_e32 v130, 0x1c000, v219
	ds_read_b128 v[148:151], v130
	ds_read_b128 v[152:155], v130 offset:1024
	ds_read_b128 v[156:159], v130 offset:2048
	ds_read_b128 v[160:163], v130 offset:3072
	ds_read_b128 v[164:167], v220 offset:32768
	ds_read_b128 v[168:171], v220 offset:33792
	ds_read_b128 v[172:175], v220 offset:34816
	ds_read_b128 v[176:179], v220 offset:35840
	ds_read_b128 v[180:183], v220 offset:36864
	ds_read_b128 v[184:187], v220 offset:37888
	ds_read_b128 v[188:191], v220 offset:38912
	ds_read_b128 v[192:195], v220 offset:39936
	s_mov_b32 m0, s41
	s_nop 0
	global_load_lds_dwordx4 v1, s[10:11]
	s_nop 1
	s_nop 0
	s_mov_b32 m0, s3
	s_nop 0
	global_load_lds_dwordx4 v217, s[10:11]
	s_nop 1
	s_add_u32 s10, s10, 0x80000
	s_addc_u32 s11, s11, 0
	s_mov_b32 m0, s64
	s_nop 0
	global_load_lds_dwordx4 v1, s[10:11]
	s_nop 1
	s_nop 0
	s_mov_b32 m0, s65
	s_nop 0
	global_load_lds_dwordx4 v217, s[10:11]
	s_nop 1
	s_waitcnt vmcnt(8)
	s_waitcnt lgkmcnt(0)
	s_setprio 1
	s_barrier
; #define PG8_STAGE(bufoff, gbase, voff) do { _Pragma("unroll") for (int _i = 0; _i < 2; ++_i) { \
;         const unsigned m0v_ = (unsigned)(uintptr_t)(lds + (bufoff) + ldsw + _i * 8192); \
;         asm volatile("s_mov_b32 m0, %0\n\ts_nop 0\n\tglobal_load_lds_dwordx4 %1, %2\n\ts_nop 1" :: "s"(m0v_), "v"((voff)[_i]), "s"((const char*)(gbase)) : "m0", "memory"); } } while (0)
; #define PG8_LDA(dst, b, h) do { _Pragma("unroll") for (int m = 0; m < 4; ++m) _Pragma("unroll") for (int k = 0; k < 2; ++k) dst[m][k] = *(const LAS bf16x8*)(lds + PG8_SA(b, h) + aoff + m * 2048 + k * 1024); } while (0)
; #define PG8_MMA(ai, bj, At, Bt) do { _Pragma("unroll") for (int m = 0; m < 4; ++m) _Pragma("unroll") for (int n = 0; n < 2; ++n) _Pragma("unroll") for (int k = 0; k < 2; ++k) \
;         acc[ai][bj][m][n] = __builtin_amdgcn_mfma_f32_16x16x32_bf16(Bt[n][k], At[m][k], acc[ai][bj][m][n], 0, 0, 0); } while (0)
; #define PG8_WAIT_V(n) asm volatile("s_waitcnt vmcnt(" #n ")" ::: "memory")
; #define PG8_WAIT_L(n) asm volatile("s_waitcnt lgkmcnt(" #n ")" ::: "memory")
; #define PG8_BAR __builtin_amdgcn_s_barrier()
; #define PG8_SCHED __builtin_amdgcn_sched_barrier(0)
; template <class Prob, class Epi, class Sched>
; __device__ __forceinline__ void gemm_phase(LAS unsigned char* lds, const Prob& P, const Sched& S, const Epi& E) {
;     ...
;             PG8_WAIT_V(8); PG8_WAIT_L(0); PG8_BAR; __builtin_amdgcn_s_setprio(1); PG8_MMA(0, 0, At, B0); PG8_MMA(0, 1, At, B1); __builtin_amdgcn_s_setprio(0); PG8_BAR; PG8_SCHED;
;             PG8_LDA(At, 1, 1); PG8_STAGE(PG8_SB(1, 0), b3, voffB); PG8_STAGE(PG8_SB(1, 1), b3 + hstepB, voffB); PG8_STAGE(PG8_SA(1, 0), a3, voffA);
;             PG8_WAIT_V(8); PG8_WAIT_L(0); PG8_BAR; __builtin_amdgcn_s_setprio(1); PG8_MMA(1, 0, At, B0); PG8_MMA(1, 1, At, B1); __builtin_amdgcn_s_setprio(0); PG8_BAR; PG8_SCHED;
;         }
	v_mfma_f32_16x16x32_bf16 v[2:5], v[132:135], v[164:167], v[2:5]
	v_mfma_f32_16x16x32_bf16 v[62:65], v[140:143], v[164:167], v[62:65]
	v_mfma_f32_16x16x32_bf16 v[58:61], v[132:135], v[172:175], v[58:61]
	v_mfma_f32_16x16x32_bf16 v[54:57], v[140:143], v[172:175], v[54:57]
	v_mfma_f32_16x16x32_bf16 v[50:53], v[132:135], v[180:183], v[50:53]
	v_mfma_f32_16x16x32_bf16 v[46:49], v[140:143], v[180:183], v[46:49]
	v_mfma_f32_16x16x32_bf16 v[42:45], v[132:135], v[188:191], v[42:45]
	v_mfma_f32_16x16x32_bf16 v[38:41], v[140:143], v[188:191], v[38:41]
	v_mfma_f32_16x16x32_bf16 v[34:37], v[148:151], v[164:167], v[34:37]
	v_mfma_f32_16x16x32_bf16 v[30:33], v[156:159], v[164:167], v[30:33]
	v_mfma_f32_16x16x32_bf16 v[26:29], v[148:151], v[172:175], v[26:29]
	v_mfma_f32_16x16x32_bf16 v[22:25], v[156:159], v[172:175], v[22:25]
	v_mfma_f32_16x16x32_bf16 v[18:21], v[148:151], v[180:183], v[18:21]
	v_mfma_f32_16x16x32_bf16 v[14:17], v[156:159], v[180:183], v[14:17]
	v_mfma_f32_16x16x32_bf16 v[10:13], v[148:151], v[188:191], v[10:13]
	v_mfma_f32_16x16x32_bf16 v[6:9], v[156:159], v[188:191], v[6:9]
	v_mfma_f32_16x16x32_bf16 v[2:5], v[136:139], v[168:171], v[2:5]
	v_mfma_f32_16x16x32_bf16 v[62:65], v[144:147], v[168:171], v[62:65]
	v_mfma_f32_16x16x32_bf16 v[58:61], v[136:139], v[176:179], v[58:61]
	v_mfma_f32_16x16x32_bf16 v[54:57], v[144:147], v[176:179], v[54:57]
	v_mfma_f32_16x16x32_bf16 v[50:53], v[136:139], v[184:187], v[50:53]
	v_mfma_f32_16x16x32_bf16 v[46:49], v[144:147], v[184:187], v[46:49]
	v_mfma_f32_16x16x32_bf16 v[42:45], v[136:139], v[192:195], v[42:45]
	v_mfma_f32_16x16x32_bf16 v[38:41], v[144:147], v[192:195], v[38:41]
	v_mfma_f32_16x16x32_bf16 v[34:37], v[152:155], v[168:171], v[34:37]
	v_mfma_f32_16x16x32_bf16 v[30:33], v[160:163], v[168:171], v[30:33]
	v_mfma_f32_16x16x32_bf16 v[26:29], v[152:155], v[176:179], v[26:29]
	v_mfma_f32_16x16x32_bf16 v[22:25], v[160:163], v[176:179], v[22:25]
	v_mfma_f32_16x16x32_bf16 v[18:21], v[152:155], v[184:187], v[18:21]
	v_mfma_f32_16x16x32_bf16 v[14:17], v[160:163], v[184:187], v[14:17]
	v_mfma_f32_16x16x32_bf16 v[10:13], v[152:155], v[192:195], v[10:13]
	v_mfma_f32_16x16x32_bf16 v[6:9], v[160:163], v[192:195], v[6:9]
	s_barrier
	s_setprio 0
	ds_read_b128 v[164:167], v220 offset:49152
	ds_read_b128 v[168:171], v220 offset:50176
	ds_read_b128 v[172:175], v220 offset:51200
	ds_read_b128 v[176:179], v220 offset:52224
	ds_read_b128 v[180:183], v220 offset:53248
	ds_read_b128 v[184:187], v220 offset:54272
	ds_read_b128 v[188:191], v220 offset:55296
	ds_read_b128 v[192:195], v220 offset:56320
	s_add_u32 s10, s8, 0x80
	s_addc_u32 s11, s9, 0
	s_mov_b32 m0, s62
	s_nop 0
	global_load_lds_dwordx4 v216, s[10:11]
	s_nop 1
	s_add_u32 s8, s8, 0x80080
	s_mov_b32 m0, s63
	s_nop 0
	global_load_lds_dwordx4 v218, s[10:11]
	s_nop 1
	s_addc_u32 s9, s9, 0
	s_mov_b32 m0, s44
	s_nop 0
	global_load_lds_dwordx4 v216, s[8:9]
	s_nop 1
	s_nop 0
	s_mov_b32 m0, s45
	s_nop 0
	global_load_lds_dwordx4 v218, s[8:9]
	s_nop 1
	s_nop 0
	s_waitcnt vmcnt(6)
	s_waitcnt lgkmcnt(0)
	s_setprio 1
	s_barrier
	v_mfma_f32_16x16x32_bf16 v[126:129], v[132:135], v[164:167], v[126:129]
	v_mfma_f32_16x16x32_bf16 v[122:125], v[140:143], v[164:167], v[122:125]
	s_add_u32 s4, s4, 0x100
	v_mfma_f32_16x16x32_bf16 v[118:121], v[132:135], v[172:175], v[118:121]
	s_addc_u32 s5, s5, 0
	v_mfma_f32_16x16x32_bf16 v[114:117], v[140:143], v[172:175], v[114:117]
	s_mov_b32 s6, s68
	v_mfma_f32_16x16x32_bf16 v[110:113], v[132:135], v[180:183], v[110:113]
	v_mfma_f32_16x16x32_bf16 v[106:109], v[140:143], v[180:183], v[106:109]
	v_mfma_f32_16x16x32_bf16 v[102:105], v[132:135], v[188:191], v[102:105]
	v_mfma_f32_16x16x32_bf16 v[98:101], v[140:143], v[188:191], v[98:101]
	v_mfma_f32_16x16x32_bf16 v[94:97], v[148:151], v[164:167], v[94:97]
	v_mfma_f32_16x16x32_bf16 v[90:93], v[156:159], v[164:167], v[90:93]
	v_mfma_f32_16x16x32_bf16 v[86:89], v[148:151], v[172:175], v[86:89]
	v_mfma_f32_16x16x32_bf16 v[82:85], v[156:159], v[172:175], v[82:85]
	v_mfma_f32_16x16x32_bf16 v[78:81], v[148:151], v[180:183], v[78:81]
	v_mfma_f32_16x16x32_bf16 v[74:77], v[156:159], v[180:183], v[74:77]
	v_mfma_f32_16x16x32_bf16 v[70:73], v[148:151], v[188:191], v[70:73]
	v_mfma_f32_16x16x32_bf16 v[66:69], v[156:159], v[188:191], v[66:69]
	v_mfma_f32_16x16x32_bf16 v[126:129], v[136:139], v[168:171], v[126:129]
	v_mfma_f32_16x16x32_bf16 v[122:125], v[144:147], v[168:171], v[122:125]
	v_mfma_f32_16x16x32_bf16 v[118:121], v[136:139], v[176:179], v[118:121]
	v_mfma_f32_16x16x32_bf16 v[114:117], v[144:147], v[176:179], v[114:117]
	v_mfma_f32_16x16x32_bf16 v[110:113], v[136:139], v[184:187], v[110:113]
	v_mfma_f32_16x16x32_bf16 v[106:109], v[144:147], v[184:187], v[106:109]
	v_mfma_f32_16x16x32_bf16 v[102:105], v[136:139], v[192:195], v[102:105]
	v_mfma_f32_16x16x32_bf16 v[98:101], v[144:147], v[192:195], v[98:101]
	v_mfma_f32_16x16x32_bf16 v[94:97], v[152:155], v[168:171], v[94:97]
	v_mfma_f32_16x16x32_bf16 v[90:93], v[160:163], v[168:171], v[90:93]
	v_mfma_f32_16x16x32_bf16 v[86:89], v[152:155], v[176:179], v[86:89]
	v_mfma_f32_16x16x32_bf16 v[82:85], v[160:163], v[176:179], v[82:85]
	v_mfma_f32_16x16x32_bf16 v[78:81], v[152:155], v[184:187], v[78:81]
	v_mfma_f32_16x16x32_bf16 v[74:77], v[160:163], v[184:187], v[74:77]
	v_mfma_f32_16x16x32_bf16 v[70:73], v[152:155], v[192:195], v[70:73]
	v_mfma_f32_16x16x32_bf16 v[66:69], v[160:163], v[192:195], v[66:69]
	s_barrier
	s_setprio 0
	s_cmp_ge_i32 s68, s53
	s_cbranch_scc0 .LBB0_451
	v_readlane_b32 s4, v247, 39
	v_readlane_b32 s5, v247, 40
	s_and_b64 vcc, exec, s[4:5]
	s_cbranch_vccz .LBB0_454
	s_barrier

; #define PG8_STAGE(bufoff, gbase, voff) do { _Pragma("unroll") for (int _i = 0; _i < 2; ++_i) { \
;         const unsigned m0v_ = (unsigned)(uintptr_t)(lds + (bufoff) + ldsw + _i * 8192); \
;         asm volatile("s_mov_b32 m0, %0\n\ts_nop 0\n\tglobal_load_lds_dwordx4 %1, %2\n\ts_nop 1" :: "s"(m0v_), "v"((voff)[_i]), "s"((const char*)(gbase)) : "m0", "memory"); } } while (0)
; #define PG8_LDA(dst, b, h) do { _Pragma("unroll") for (int m = 0; m < 4; ++m) _Pragma("unroll") for (int k = 0; k < 2; ++k) dst[m][k] = *(const LAS bf16x8*)(lds + PG8_SA(b, h) + aoff + m * 2048 + k * 1024); } while (0)
; #define PG8_LDB(dst, b, h) do { _Pragma("unroll") for (int n = 0; n < 2; ++n) _Pragma("unroll") for (int k = 0; k < 2; ++k) dst[n][k] = *(const LAS bf16x8*)(lds + PG8_SB(b, h) + boff + n * 2048 + k * 1024); } while (0)
; #define PG8_MMA(ai, bj, At, Bt) do { _Pragma("unroll") for (int m = 0; m < 4; ++m) _Pragma("unroll") for (int n = 0; n < 2; ++n) _Pragma("unroll") for (int k = 0; k < 2; ++k) \
;         acc[ai][bj][m][n] = __builtin_amdgcn_mfma_f32_16x16x32_bf16(Bt[n][k], At[m][k], acc[ai][bj][m][n], 0, 0, 0); } while (0)
; template <class Prob, class Epi, class Sched>
; __device__ __forceinline__ void gemm_phase(LAS unsigned char* lds, const Prob& P, const Sched& S, const Epi& E) {
;     ...
;         for (int t = 0; t < nt; t += 2) {
;             const bool last = (t == nt - 2);
;             if (Epi::MID_T >= 0) { if (t == Epi::MID_T) E.mid(acc, cur, slot, wr, wc, fr, fq, lds); }
;             const char* a1 = cA + (size_t)(t + 1) * kstep;
;             const char* a2 = last ? nA : cA + (size_t)(t + 2) * kstep; const char* b2 = last ? nB : cB + (size_t)(t + 2) * kstep;
;             const char* a3 = a2 + kstep; const char* b3 = b2 + kstep;
;             PG8_LDB(B0, 0, 0); PG8_LDB(B1, 0, 1); PG8_SCHED; PG8_LDA(At, 0, 0); PG8_STAGE(PG8_SA(1, 1), a1 + hstepA, voffA);
;             PG8_WAIT_V(8); PG8_WAIT_L(0); PG8_BAR; __builtin_amdgcn_s_setprio(1); PG8_MMA(0, 0, At, B0); PG8_MMA(0, 1, At, B1); __builtin_amdgcn_s_setprio(0); PG8_BAR; PG8_SCHED;
;             PG8_LDA(At, 0, 1); PG8_STAGE(PG8_SB(0, 0), b2, voffB); PG8_STAGE(PG8_SB(0, 1), b2 + hstepB, voffB); PG8_STAGE(PG8_SA(0, 0), a2, voffA);
;             PG8_WAIT_V(8); PG8_WAIT_L(0); PG8_BAR; __builtin_amdgcn_s_setprio(1); PG8_MMA(1, 0, At, B0); PG8_MMA(1, 1, At, B1); __builtin_amdgcn_s_setprio(0); PG8_BAR; PG8_SCHED;
.LBB0_866:
	v_add_u32_e32 v130, 0x10000, v143
	ds_read_b128 v[136:139], v130
	ds_read_b128 v[148:151], v130 offset:1024
	ds_read_b128 v[152:155], v130 offset:2048
	ds_read_b128 v[156:159], v130 offset:3072
	v_add_u32_e32 v130, 0x14000, v143
	ds_read_b128 v[160:163], v130
	ds_read_b128 v[164:167], v130 offset:1024
	ds_read_b128 v[168:171], v130 offset:2048
	ds_read_b128 v[172:175], v130 offset:3072
	ds_read_b128 v[176:179], v144
	ds_read_b128 v[180:183], v144 offset:1024
	ds_read_b128 v[184:187], v144 offset:2048
	ds_read_b128 v[188:191], v144 offset:3072
	ds_read_b128 v[192:195], v144 offset:4096
	ds_read_b128 v[196:199], v144 offset:5120
	ds_read_b128 v[200:203], v144 offset:6144
	ds_read_b128 v[204:207], v144 offset:7168
	s_sub_u32 s98, s4, 0x80000
	s_subb_u32 s99, s5, 0
	s_mov_b32 m0, s69
	s_nop 0
	global_load_lds_dwordx4 v1, s[98:99]
	s_nop 1
	s_nop 0
	s_mov_b32 m0, s70
	s_nop 0
	global_load_lds_dwordx4 v141, s[98:99]
	s_nop 1
	s_mov_b32 m0, s74
	s_nop 0
	global_load_lds_dwordx4 v1, s[4:5]
	s_nop 1
	s_nop 0
	s_mov_b32 m0, s75
	s_nop 0
	global_load_lds_dwordx4 v141, s[4:5]
	s_nop 1
	s_waitcnt vmcnt(8)
	s_waitcnt lgkmcnt(0)
	s_setprio 1
	s_barrier
	v_mfma_f32_16x16x32_bf16 v[2:5], v[136:139], v[176:179], v[2:5]
	v_mfma_f32_16x16x32_bf16 v[22:25], v[152:155], v[176:179], v[22:25]
	s_cmp_eq_u32 s83, 28
	v_mfma_f32_16x16x32_bf16 v[6:9], v[136:139], v[184:187], v[6:9]
	s_cselect_b32 s64, s48, s47
	v_mfma_f32_16x16x32_bf16 v[26:29], v[152:155], v[184:187], v[26:29]
	s_cselect_b32 s65, s49, s80
	v_mfma_f32_16x16x32_bf16 v[14:17], v[136:139], v[192:195], v[14:17]
	s_cselect_b32 s62, s50, s81
	v_mfma_f32_16x16x32_bf16 v[42:45], v[152:155], v[192:195], v[42:45]
	s_cselect_b32 s63, s51, s82
	v_mfma_f32_16x16x32_bf16 v[34:37], v[136:139], v[200:203], v[34:37]
	s_add_u32 s54, s64, 0x80
	v_mfma_f32_16x16x32_bf16 v[54:57], v[152:155], v[200:203], v[54:57]
	s_addc_u32 s55, s65, 0
	v_mfma_f32_16x16x32_bf16 v[10:13], v[160:163], v[176:179], v[10:13]
	v_mfma_f32_16x16x32_bf16 v[30:33], v[168:171], v[176:179], v[30:33]
	v_mfma_f32_16x16x32_bf16 v[18:21], v[160:163], v[184:187], v[18:21]
	v_mfma_f32_16x16x32_bf16 v[46:49], v[168:171], v[184:187], v[46:49]
	v_mfma_f32_16x16x32_bf16 v[38:41], v[160:163], v[192:195], v[38:41]
	v_mfma_f32_16x16x32_bf16 v[58:61], v[168:171], v[192:195], v[58:61]
	v_mfma_f32_16x16x32_bf16 v[50:53], v[160:163], v[200:203], v[50:53]
	v_mfma_f32_16x16x32_bf16 v[66:69], v[168:171], v[200:203], v[66:69]
	v_mfma_f32_16x16x32_bf16 v[2:5], v[148:151], v[180:183], v[2:5]
	v_mfma_f32_16x16x32_bf16 v[22:25], v[156:159], v[180:183], v[22:25]
	v_mfma_f32_16x16x32_bf16 v[6:9], v[148:151], v[188:191], v[6:9]
	v_mfma_f32_16x16x32_bf16 v[26:29], v[156:159], v[188:191], v[26:29]
	v_mfma_f32_16x16x32_bf16 v[14:17], v[148:151], v[196:199], v[14:17]
	v_mfma_f32_16x16x32_bf16 v[42:45], v[156:159], v[196:199], v[42:45]
	v_mfma_f32_16x16x32_bf16 v[34:37], v[148:151], v[204:207], v[34:37]
	v_mfma_f32_16x16x32_bf16 v[54:57], v[156:159], v[204:207], v[54:57]
	v_mfma_f32_16x16x32_bf16 v[10:13], v[164:167], v[180:183], v[10:13]
	v_mfma_f32_16x16x32_bf16 v[30:33], v[172:175], v[180:183], v[30:33]
	v_mfma_f32_16x16x32_bf16 v[18:21], v[164:167], v[188:191], v[18:21]
	v_mfma_f32_16x16x32_bf16 v[46:49], v[172:175], v[188:191], v[46:49]
	v_mfma_f32_16x16x32_bf16 v[38:41], v[164:167], v[196:199], v[38:41]
	v_mfma_f32_16x16x32_bf16 v[58:61], v[172:175], v[196:199], v[58:61]
	v_mfma_f32_16x16x32_bf16 v[50:53], v[164:167], v[204:207], v[50:53]
	v_mfma_f32_16x16x32_bf16 v[66:69], v[172:175], v[204:207], v[66:69]
	s_barrier
	s_setprio 0
	ds_read_b128 v[176:179], v144 offset:16384
	ds_read_b128 v[180:183], v144 offset:17408
	ds_read_b128 v[184:187], v144 offset:18432
	ds_read_b128 v[188:191], v144 offset:19456
	ds_read_b128 v[192:195], v144 offset:20480
	ds_read_b128 v[196:199], v144 offset:21504
	ds_read_b128 v[200:203], v144 offset:22528
	ds_read_b128 v[204:207], v144 offset:23552
	s_mov_b32 m0, s41
	s_nop 0
	global_load_lds_dwordx4 v140, s[62:63]
	s_nop 1
	s_add_u32 s84, s62, 0x80000
	s_mov_b32 m0, s53
	s_nop 0
	global_load_lds_dwordx4 v142, s[62:63]
	s_nop 1
	s_addc_u32 s85, s63, 0
	s_mov_b32 m0, s56
	s_nop 0
	global_load_lds_dwordx4 v140, s[84:85]
	s_nop 1
	s_nop 0
	s_mov_b32 m0, s57
	s_nop 0
	global_load_lds_dwordx4 v142, s[84:85]
	s_nop 1
	s_nop 0
	s_waitcnt vmcnt(6)
	s_waitcnt lgkmcnt(0)
	s_setprio 1
	s_barrier
	v_mfma_f32_16x16x32_bf16 v[62:65], v[136:139], v[176:179], v[62:65]
	v_mfma_f32_16x16x32_bf16 v[78:81], v[152:155], v[176:179], v[78:81]
	v_mfma_f32_16x16x32_bf16 v[70:73], v[136:139], v[184:187], v[70:73]
	v_mfma_f32_16x16x32_bf16 v[90:93], v[152:155], v[184:187], v[90:93]
	v_mfma_f32_16x16x32_bf16 v[82:85], v[136:139], v[192:195], v[82:85]
	v_mfma_f32_16x16x32_bf16 v[106:109], v[152:155], v[192:195], v[106:109]
	v_mfma_f32_16x16x32_bf16 v[98:101], v[136:139], v[200:203], v[98:101]
	v_mfma_f32_16x16x32_bf16 v[118:121], v[152:155], v[200:203], v[118:121]
	v_mfma_f32_16x16x32_bf16 v[74:77], v[160:163], v[176:179], v[74:77]
	v_mfma_f32_16x16x32_bf16 v[94:97], v[168:171], v[176:179], v[94:97]
	v_mfma_f32_16x16x32_bf16 v[86:89], v[160:163], v[184:187], v[86:89]
	v_mfma_f32_16x16x32_bf16 v[110:113], v[168:171], v[184:187], v[110:113]
	v_mfma_f32_16x16x32_bf16 v[102:105], v[160:163], v[192:195], v[102:105]
	v_mfma_f32_16x16x32_bf16 v[122:125], v[168:171], v[192:195], v[122:125]
	v_mfma_f32_16x16x32_bf16 v[114:117], v[160:163], v[200:203], v[114:117]
	v_mfma_f32_16x16x32_bf16 v[126:129], v[168:171], v[200:203], v[126:129]
	v_mfma_f32_16x16x32_bf16 v[62:65], v[148:151], v[180:183], v[62:65]
	v_mfma_f32_16x16x32_bf16 v[78:81], v[156:159], v[180:183], v[78:81]
	v_mfma_f32_16x16x32_bf16 v[70:73], v[148:151], v[188:191], v[70:73]
	v_mfma_f32_16x16x32_bf16 v[90:93], v[156:159], v[188:191], v[90:93]
	v_mfma_f32_16x16x32_bf16 v[82:85], v[148:151], v[196:199], v[82:85]
	v_mfma_f32_16x16x32_bf16 v[106:109], v[156:159], v[196:199], v[106:109]
	v_mfma_f32_16x16x32_bf16 v[98:101], v[148:151], v[204:207], v[98:101]
	v_mfma_f32_16x16x32_bf16 v[118:121], v[156:159], v[204:207], v[118:121]
	v_mfma_f32_16x16x32_bf16 v[74:77], v[164:167], v[180:183], v[74:77]
	v_mfma_f32_16x16x32_bf16 v[94:97], v[172:175], v[180:183], v[94:97]
	v_mfma_f32_16x16x32_bf16 v[86:89], v[164:167], v[188:191], v[86:89]
	v_mfma_f32_16x16x32_bf16 v[110:113], v[172:175], v[188:191], v[110:113]
	v_mfma_f32_16x16x32_bf16 v[102:105], v[164:167], v[196:199], v[102:105]
	v_mfma_f32_16x16x32_bf16 v[122:125], v[172:175], v[196:199], v[122:125]
	v_mfma_f32_16x16x32_bf16 v[114:117], v[164:167], v[204:207], v[114:117]
	v_mfma_f32_16x16x32_bf16 v[126:129], v[172:175], v[204:207], v[126:129]
	s_barrier
; #define PG8_STAGE(bufoff, gbase, voff) do { _Pragma("unroll") for (int _i = 0; _i < 2; ++_i) { \
;         const unsigned m0v_ = (unsigned)(uintptr_t)(lds + (bufoff) + ldsw + _i * 8192); \
;         asm volatile("s_mov_b32 m0, %0\n\ts_nop 0\n\tglobal_load_lds_dwordx4 %1, %2\n\ts_nop 1" :: "s"(m0v_), "v"((voff)[_i]), "s"((const char*)(gbase)) : "m0", "memory"); } } while (0)
; #define PG8_LDA(dst, b, h) do { _Pragma("unroll") for (int m = 0; m < 4; ++m) _Pragma("unroll") for (int k = 0; k < 2; ++k) dst[m][k] = *(const LAS bf16x8*)(lds + PG8_SA(b, h) + aoff + m * 2048 + k * 1024); } while (0)
; #define PG8_LDB(dst, b, h) do { _Pragma("unroll") for (int n = 0; n < 2; ++n) _Pragma("unroll") for (int k = 0; k < 2; ++k) dst[n][k] = *(const LAS bf16x8*)(lds + PG8_SB(b, h) + boff + n * 2048 + k * 1024); } while (0)
; #define PG8_MMA(ai, bj, At, Bt) do { _Pragma("unroll") for (int m = 0; m < 4; ++m) _Pragma("unroll") for (int n = 0; n < 2; ++n) _Pragma("unroll") for (int k = 0; k < 2; ++k) \
;         acc[ai][bj][m][n] = __builtin_amdgcn_mfma_f32_16x16x32_bf16(Bt[n][k], At[m][k], acc[ai][bj][m][n], 0, 0, 0); } while (0)
; #define PG8_WAIT_V(n) asm volatile("s_waitcnt vmcnt(" #n ")" ::: "memory")
; #define PG8_WAIT_L(n) asm volatile("s_waitcnt lgkmcnt(" #n ")" ::: "memory")
; #define PG8_BAR __builtin_amdgcn_s_barrier()
; #define PG8_SCHED __builtin_amdgcn_sched_barrier(0)
; template <class Prob, class Epi, class Sched>
; __device__ __forceinline__ void gemm_phase(LAS unsigned char* lds, const Prob& P, const Sched& S, const Epi& E) {
;     ...
;             PG8_LDB(B0, 1, 0); PG8_LDB(B1, 1, 1); PG8_SCHED; PG8_LDA(At, 1, 0); PG8_STAGE(PG8_SA(0, 1), a2 + hstepA, voffA);
;             PG8_WAIT_V(8); PG8_WAIT_L(0); PG8_BAR; __builtin_amdgcn_s_setprio(1); PG8_MMA(0, 0, At, B0); PG8_MMA(0, 1, At, B1); __builtin_amdgcn_s_setprio(0); PG8_BAR; PG8_SCHED;
;             PG8_LDA(At, 1, 1); PG8_STAGE(PG8_SB(1, 0), b3, voffB); PG8_STAGE(PG8_SB(1, 1), b3 + hstepB, voffB); PG8_STAGE(PG8_SA(1, 0), a3, voffA);
;             PG8_WAIT_V(8); PG8_WAIT_L(0); PG8_BAR; __builtin_amdgcn_s_setprio(1); PG8_MMA(1, 0, At, B0); PG8_MMA(1, 1, At, B1); __builtin_amdgcn_s_setprio(0); PG8_BAR; PG8_SCHED;
;         }
	s_setprio 0
	v_add_u32_e32 v130, 0x18000, v143
	ds_read_b128 v[136:139], v130
	ds_read_b128 v[148:151], v130 offset:1024
	ds_read_b128 v[152:155], v130 offset:2048
	ds_read_b128 v[156:159], v130 offset:3072
	v_add_u32_e32 v130, 0x1c000, v143
	ds_read_b128 v[160:163], v130
	ds_read_b128 v[164:167], v130 offset:1024
	ds_read_b128 v[168:171], v130 offset:2048
	ds_read_b128 v[172:175], v130 offset:3072
	ds_read_b128 v[176:179], v144 offset:32768
	ds_read_b128 v[180:183], v144 offset:33792
	ds_read_b128 v[184:187], v144 offset:34816
	ds_read_b128 v[188:191], v144 offset:35840
	ds_read_b128 v[192:195], v144 offset:36864
	ds_read_b128 v[196:199], v144 offset:37888
	ds_read_b128 v[200:203], v144 offset:38912
	ds_read_b128 v[204:207], v144 offset:39936
	s_mov_b32 m0, s34
	s_nop 0
	global_load_lds_dwordx4 v1, s[64:65]
	s_nop 1
	s_nop 0
	s_mov_b32 m0, s58
	s_nop 0
	global_load_lds_dwordx4 v141, s[64:65]
	s_nop 1
	s_add_u32 s64, s64, 0x80000
	s_addc_u32 s65, s65, 0
	s_mov_b32 m0, s59
	s_nop 0
	global_load_lds_dwordx4 v1, s[64:65]
	s_nop 1
	s_nop 0
	s_mov_b32 m0, s60
	s_nop 0
	global_load_lds_dwordx4 v141, s[64:65]
	s_nop 1
	s_waitcnt vmcnt(8)
	s_waitcnt lgkmcnt(0)
	s_setprio 1
	s_barrier
	v_mfma_f32_16x16x32_bf16 v[2:5], v[136:139], v[176:179], v[2:5]
	v_mfma_f32_16x16x32_bf16 v[22:25], v[152:155], v[176:179], v[22:25]
	v_mfma_f32_16x16x32_bf16 v[6:9], v[136:139], v[184:187], v[6:9]
	v_mfma_f32_16x16x32_bf16 v[26:29], v[152:155], v[184:187], v[26:29]
	v_mfma_f32_16x16x32_bf16 v[14:17], v[136:139], v[192:195], v[14:17]
	v_mfma_f32_16x16x32_bf16 v[42:45], v[152:155], v[192:195], v[42:45]
	v_mfma_f32_16x16x32_bf16 v[34:37], v[136:139], v[200:203], v[34:37]
	v_mfma_f32_16x16x32_bf16 v[54:57], v[152:155], v[200:203], v[54:57]
	v_mfma_f32_16x16x32_bf16 v[10:13], v[160:163], v[176:179], v[10:13]
	v_mfma_f32_16x16x32_bf16 v[30:33], v[168:171], v[176:179], v[30:33]
	v_mfma_f32_16x16x32_bf16 v[18:21], v[160:163], v[184:187], v[18:21]
	v_mfma_f32_16x16x32_bf16 v[46:49], v[168:171], v[184:187], v[46:49]
	v_mfma_f32_16x16x32_bf16 v[38:41], v[160:163], v[192:195], v[38:41]
	v_mfma_f32_16x16x32_bf16 v[58:61], v[168:171], v[192:195], v[58:61]
	v_mfma_f32_16x16x32_bf16 v[50:53], v[160:163], v[200:203], v[50:53]
	v_mfma_f32_16x16x32_bf16 v[66:69], v[168:171], v[200:203], v[66:69]
	v_mfma_f32_16x16x32_bf16 v[2:5], v[148:151], v[180:183], v[2:5]
	v_mfma_f32_16x16x32_bf16 v[22:25], v[156:159], v[180:183], v[22:25]
	v_mfma_f32_16x16x32_bf16 v[6:9], v[148:151], v[188:191], v[6:9]
	v_mfma_f32_16x16x32_bf16 v[26:29], v[156:159], v[188:191], v[26:29]
	v_mfma_f32_16x16x32_bf16 v[14:17], v[148:151], v[196:199], v[14:17]
	v_mfma_f32_16x16x32_bf16 v[42:45], v[156:159], v[196:199], v[42:45]
	v_mfma_f32_16x16x32_bf16 v[34:37], v[148:151], v[204:207], v[34:37]
	v_mfma_f32_16x16x32_bf16 v[54:57], v[156:159], v[204:207], v[54:57]
	v_mfma_f32_16x16x32_bf16 v[10:13], v[164:167], v[180:183], v[10:13]
	v_mfma_f32_16x16x32_bf16 v[30:33], v[172:175], v[180:183], v[30:33]
	v_mfma_f32_16x16x32_bf16 v[18:21], v[164:167], v[188:191], v[18:21]
	v_mfma_f32_16x16x32_bf16 v[46:49], v[172:175], v[188:191], v[46:49]
	v_mfma_f32_16x16x32_bf16 v[38:41], v[164:167], v[196:199], v[38:41]
	v_mfma_f32_16x16x32_bf16 v[58:61], v[172:175], v[196:199], v[58:61]
	v_mfma_f32_16x16x32_bf16 v[50:53], v[164:167], v[204:207], v[50:53]
	v_mfma_f32_16x16x32_bf16 v[66:69], v[172:175], v[204:207], v[66:69]
	s_barrier
	s_setprio 0
	ds_read_b128 v[176:179], v144 offset:49152
	ds_read_b128 v[180:183], v144 offset:50176
	ds_read_b128 v[184:187], v144 offset:51200
	ds_read_b128 v[188:191], v144 offset:52224
	ds_read_b128 v[192:195], v144 offset:53248
	ds_read_b128 v[196:199], v144 offset:54272
	ds_read_b128 v[200:203], v144 offset:55296
	ds_read_b128 v[204:207], v144 offset:56320
	s_add_u32 s64, s62, 0x80
	s_addc_u32 s65, s63, 0
	s_mov_b32 m0, s67
	s_nop 0
	global_load_lds_dwordx4 v140, s[64:65]
	s_nop 1
	s_add_u32 s62, s62, 0x80080
	s_mov_b32 m0, s68
	s_nop 0
	global_load_lds_dwordx4 v142, s[64:65]
	s_nop 1
	s_addc_u32 s63, s63, 0
	s_mov_b32 m0, s71
	s_nop 0
	global_load_lds_dwordx4 v140, s[62:63]
	s_nop 1
	s_nop 0
	s_mov_b32 m0, s72
	s_nop 0
	global_load_lds_dwordx4 v142, s[62:63]
	s_nop 1
	s_nop 0
	s_waitcnt vmcnt(6)
	s_waitcnt lgkmcnt(0)
	s_setprio 1
	s_barrier
	v_mfma_f32_16x16x32_bf16 v[62:65], v[136:139], v[176:179], v[62:65]
	v_mfma_f32_16x16x32_bf16 v[78:81], v[152:155], v[176:179], v[78:81]
	s_add_i32 s83, s83, 2
	v_mfma_f32_16x16x32_bf16 v[70:73], v[136:139], v[184:187], v[70:73]
	s_add_u32 s47, s47, 0x100
	v_mfma_f32_16x16x32_bf16 v[90:93], v[152:155], v[184:187], v[90:93]
	s_addc_u32 s80, s80, 0
	v_mfma_f32_16x16x32_bf16 v[82:85], v[136:139], v[192:195], v[82:85]
	s_add_u32 s81, s81, 0x100
	v_mfma_f32_16x16x32_bf16 v[106:109], v[152:155], v[192:195], v[106:109]
	s_addc_u32 s82, s82, 0
	v_mfma_f32_16x16x32_bf16 v[98:101], v[136:139], v[200:203], v[98:101]
	s_add_u32 s4, s4, 0x100
	v_mfma_f32_16x16x32_bf16 v[118:121], v[152:155], v[200:203], v[118:121]
	s_addc_u32 s5, s5, 0
	v_mfma_f32_16x16x32_bf16 v[74:77], v[160:163], v[176:179], v[74:77]
	v_mfma_f32_16x16x32_bf16 v[94:97], v[168:171], v[176:179], v[94:97]
	v_mfma_f32_16x16x32_bf16 v[86:89], v[160:163], v[184:187], v[86:89]
	v_mfma_f32_16x16x32_bf16 v[110:113], v[168:171], v[184:187], v[110:113]
	v_mfma_f32_16x16x32_bf16 v[102:105], v[160:163], v[192:195], v[102:105]
	v_mfma_f32_16x16x32_bf16 v[122:125], v[168:171], v[192:195], v[122:125]
	v_mfma_f32_16x16x32_bf16 v[114:117], v[160:163], v[200:203], v[114:117]
	v_mfma_f32_16x16x32_bf16 v[126:129], v[168:171], v[200:203], v[126:129]
	v_mfma_f32_16x16x32_bf16 v[62:65], v[148:151], v[180:183], v[62:65]
	v_mfma_f32_16x16x32_bf16 v[78:81], v[156:159], v[180:183], v[78:81]
	v_mfma_f32_16x16x32_bf16 v[70:73], v[148:151], v[188:191], v[70:73]
	v_mfma_f32_16x16x32_bf16 v[90:93], v[156:159], v[188:191], v[90:93]
	v_mfma_f32_16x16x32_bf16 v[82:85], v[148:151], v[196:199], v[82:85]
	v_mfma_f32_16x16x32_bf16 v[106:109], v[156:159], v[196:199], v[106:109]
	v_mfma_f32_16x16x32_bf16 v[98:101], v[148:151], v[204:207], v[98:101]
	v_mfma_f32_16x16x32_bf16 v[118:121], v[156:159], v[204:207], v[118:121]
	v_mfma_f32_16x16x32_bf16 v[74:77], v[164:167], v[180:183], v[74:77]
	v_mfma_f32_16x16x32_bf16 v[94:97], v[172:175], v[180:183], v[94:97]
	v_mfma_f32_16x16x32_bf16 v[86:89], v[164:167], v[188:191], v[86:89]
	v_mfma_f32_16x16x32_bf16 v[110:113], v[172:175], v[188:191], v[110:113]
	v_mfma_f32_16x16x32_bf16 v[102:105], v[164:167], v[196:199], v[102:105]
	v_mfma_f32_16x16x32_bf16 v[122:125], v[172:175], v[196:199], v[122:125]
	v_mfma_f32_16x16x32_bf16 v[114:117], v[164:167], v[204:207], v[114:117]
	v_mfma_f32_16x16x32_bf16 v[126:129], v[172:175], v[204:207], v[126:129]
	s_barrier
	s_setprio 0
	s_cmp_gt_u32 s83, 29
	s_cbranch_scc1 .LBB0_869

; #define PG8_STAGE(bufoff, gbase, voff) do { _Pragma("unroll") for (int _i = 0; _i < 2; ++_i) { \
;         const unsigned m0v_ = (unsigned)(uintptr_t)(lds + (bufoff) + ldsw + _i * 8192); \
;         asm volatile("s_mov_b32 m0, %0\n\ts_nop 0\n\tglobal_load_lds_dwordx4 %1, %2\n\ts_nop 1" :: "s"(m0v_), "v"((voff)[_i]), "s"((const char*)(gbase)) : "m0", "memory"); } } while (0)
; #define PG8_LDA(dst, b, h) do { _Pragma("unroll") for (int m = 0; m < 4; ++m) _Pragma("unroll") for (int k = 0; k < 2; ++k) dst[m][k] = *(const LAS bf16x8*)(lds + PG8_SA(b, h) + aoff + m * 2048 + k * 1024); } while (0)
; #define PG8_LDB(dst, b, h) do { _Pragma("unroll") for (int n = 0; n < 2; ++n) _Pragma("unroll") for (int k = 0; k < 2; ++k) dst[n][k] = *(const LAS bf16x8*)(lds + PG8_SB(b, h) + boff + n * 2048 + k * 1024); } while (0)
; #define PG8_MMA(ai, bj, At, Bt) do { _Pragma("unroll") for (int m = 0; m < 4; ++m) _Pragma("unroll") for (int n = 0; n < 2; ++n) _Pragma("unroll") for (int k = 0; k < 2; ++k) \
;         acc[ai][bj][m][n] = __builtin_amdgcn_mfma_f32_16x16x32_bf16(Bt[n][k], At[m][k], acc[ai][bj][m][n], 0, 0, 0); } while (0)
; template <class Prob, class Epi, class Sched>
; __device__ __forceinline__ void gemm_phase(LAS unsigned char* lds, const Prob& P, const Sched& S, const Epi& E) {
;     ...
;         for (int t = 0; t < nt; t += 2) {
;             const bool last = (t == nt - 2);
;             if (Epi::MID_T >= 0) { if (t == Epi::MID_T) E.mid(acc, cur, slot, wr, wc, fr, fq, lds); }
;             const char* a1 = cA + (size_t)(t + 1) * kstep;
;             const char* a2 = last ? nA : cA + (size_t)(t + 2) * kstep; const char* b2 = last ? nB : cB + (size_t)(t + 2) * kstep;
;             const char* a3 = a2 + kstep; const char* b3 = b2 + kstep;
;             PG8_LDB(B0, 0, 0); PG8_LDB(B1, 0, 1); PG8_SCHED; PG8_LDA(At, 0, 0); PG8_STAGE(PG8_SA(1, 1), a1 + hstepA, voffA);
;             PG8_WAIT_V(8); PG8_WAIT_L(0); PG8_BAR; __builtin_amdgcn_s_setprio(1); PG8_MMA(0, 0, At, B0); PG8_MMA(0, 1, At, B1); __builtin_amdgcn_s_setprio(0); PG8_BAR; PG8_SCHED;
;             PG8_LDA(At, 0, 1); PG8_STAGE(PG8_SB(0, 0), b2, voffB); PG8_STAGE(PG8_SB(0, 1), b2 + hstepB, voffB); PG8_STAGE(PG8_SA(0, 0), a2, voffA);
;             PG8_WAIT_V(8); PG8_WAIT_L(0); PG8_BAR; __builtin_amdgcn_s_setprio(1); PG8_MMA(1, 0, At, B0); PG8_MMA(1, 1, At, B1); __builtin_amdgcn_s_setprio(0); PG8_BAR; PG8_SCHED;
.LBB0_963:
	ds_read_b128 v[26:29], v199
	ds_read_b128 v[62:65], v199 offset:1024
	ds_read_b128 v[138:141], v199 offset:2048
	ds_read_b128 v[142:145], v199 offset:3072
	ds_read_b128 v[146:149], v200
	ds_read_b128 v[150:153], v200 offset:1024
	ds_read_b128 v[154:157], v200 offset:2048
	ds_read_b128 v[158:161], v200 offset:3072
	ds_read_b128 v[162:165], v201
	ds_read_b128 v[166:169], v201 offset:1024
	ds_read_b128 v[170:173], v201 offset:2048
	ds_read_b128 v[174:177], v201 offset:3072
	ds_read_b128 v[178:181], v201 offset:4096
	ds_read_b128 v[182:185], v201 offset:5120
	ds_read_b128 v[206:209], v201 offset:6144
	ds_read_b128 v[210:213], v201 offset:7168
	s_sub_u32 s98, s4, 0x80000
	s_subb_u32 s99, s5, 0
	s_mov_b32 m0, s76
	s_nop 0
	global_load_lds_dwordx4 v1, s[98:99]
	s_nop 1
	s_nop 0
	s_mov_b32 m0, s77
	s_nop 0
	global_load_lds_dwordx4 v197, s[98:99]
	s_nop 1
	s_mov_b32 m0, s81
	s_nop 0
	global_load_lds_dwordx4 v1, s[4:5]
	s_nop 1
	s_nop 0
	s_mov_b32 m0, s88
	s_nop 0
	global_load_lds_dwordx4 v197, s[4:5]
	s_nop 1
	s_waitcnt vmcnt(8)
	s_waitcnt lgkmcnt(0)
	s_setprio 1
	s_barrier
	v_mfma_f32_16x16x32_bf16 v[134:137], v[26:29], v[162:165], v[134:137]
	v_mfma_f32_16x16x32_bf16 v[70:73], v[138:141], v[162:165], v[70:73]
	s_cmp_eq_u32 s65, 28
	v_mfma_f32_16x16x32_bf16 v[102:105], v[26:29], v[170:173], v[102:105]
	s_cselect_b32 s54, s58, s49
	v_mfma_f32_16x16x32_bf16 v[82:85], v[138:141], v[170:173], v[82:85]
	s_cselect_b32 s55, s59, s51
	v_mfma_f32_16x16x32_bf16 v[78:81], v[26:29], v[178:181], v[78:81]
	s_cselect_b32 s8, s60, s63
	v_mfma_f32_16x16x32_bf16 v[14:17], v[138:141], v[178:181], v[14:17]
	s_cselect_b32 s9, s61, s64
	v_mfma_f32_16x16x32_bf16 v[130:133], v[26:29], v[206:209], v[130:133]
	s_add_u32 s6, s54, 0x80
	v_mfma_f32_16x16x32_bf16 v[126:129], v[138:141], v[206:209], v[126:129]
	s_addc_u32 s7, s55, 0
	v_mfma_f32_16x16x32_bf16 v[66:69], v[146:149], v[162:165], v[66:69]
	v_mfma_f32_16x16x32_bf16 v[54:57], v[154:157], v[162:165], v[54:57]
	v_mfma_f32_16x16x32_bf16 v[98:101], v[146:149], v[170:173], v[98:101]
	v_mfma_f32_16x16x32_bf16 v[86:89], v[154:157], v[170:173], v[86:89]
	v_mfma_f32_16x16x32_bf16 v[74:77], v[146:149], v[178:181], v[74:77]
	v_mfma_f32_16x16x32_bf16 v[10:13], v[154:157], v[178:181], v[10:13]
	v_mfma_f32_16x16x32_bf16 v[122:125], v[146:149], v[206:209], v[122:125]
	v_mfma_f32_16x16x32_bf16 v[58:61], v[154:157], v[206:209], v[58:61]
	v_mfma_f32_16x16x32_bf16 v[134:137], v[62:65], v[166:169], v[134:137]
	v_mfma_f32_16x16x32_bf16 v[70:73], v[142:145], v[166:169], v[70:73]
	v_mfma_f32_16x16x32_bf16 v[102:105], v[62:65], v[174:177], v[102:105]
	v_mfma_f32_16x16x32_bf16 v[82:85], v[142:145], v[174:177], v[82:85]
	v_mfma_f32_16x16x32_bf16 v[78:81], v[62:65], v[182:185], v[78:81]
	v_mfma_f32_16x16x32_bf16 v[14:17], v[142:145], v[182:185], v[14:17]
	v_mfma_f32_16x16x32_bf16 v[130:133], v[62:65], v[210:213], v[130:133]
	v_mfma_f32_16x16x32_bf16 v[126:129], v[142:145], v[210:213], v[126:129]
	v_mfma_f32_16x16x32_bf16 v[66:69], v[150:153], v[166:169], v[66:69]
	v_mfma_f32_16x16x32_bf16 v[54:57], v[158:161], v[166:169], v[54:57]
	v_mfma_f32_16x16x32_bf16 v[98:101], v[150:153], v[174:177], v[98:101]
	v_mfma_f32_16x16x32_bf16 v[86:89], v[158:161], v[174:177], v[86:89]
	v_mfma_f32_16x16x32_bf16 v[74:77], v[150:153], v[182:185], v[74:77]
	v_mfma_f32_16x16x32_bf16 v[10:13], v[158:161], v[182:185], v[10:13]
	v_mfma_f32_16x16x32_bf16 v[122:125], v[150:153], v[210:213], v[122:125]
	v_mfma_f32_16x16x32_bf16 v[58:61], v[158:161], v[210:213], v[58:61]
	s_barrier
	s_setprio 0
	ds_read_b128 v[162:165], v201 offset:16384
	ds_read_b128 v[166:169], v201 offset:17408
	ds_read_b128 v[170:173], v201 offset:18432
	ds_read_b128 v[174:177], v201 offset:19456
	ds_read_b128 v[178:181], v201 offset:20480
	ds_read_b128 v[182:185], v201 offset:21504
	ds_read_b128 v[206:209], v201 offset:22528
	ds_read_b128 v[210:213], v201 offset:23552
	s_mov_b32 m0, s53
	s_nop 0
	global_load_lds_dwordx4 v196, s[8:9]
	s_nop 1
	s_add_u32 s90, s8, 0x80000
	s_mov_b32 m0, s56
	s_nop 0
	global_load_lds_dwordx4 v198, s[8:9]
	s_nop 1
	s_addc_u32 s91, s9, 0
	s_mov_b32 m0, s57
	s_nop 0
	global_load_lds_dwordx4 v196, s[90:91]
	s_nop 1
	s_nop 0
	s_mov_b32 m0, s66
	s_nop 0
	global_load_lds_dwordx4 v198, s[90:91]
	s_nop 1
	s_nop 0
	s_waitcnt vmcnt(6)
	s_waitcnt lgkmcnt(0)
	s_setprio 1
	s_barrier
	v_mfma_f32_16x16x32_bf16 v[118:121], v[26:29], v[162:165], v[118:121]
	v_mfma_f32_16x16x32_bf16 v[30:33], v[138:141], v[162:165], v[30:33]
	v_mfma_f32_16x16x32_bf16 v[42:45], v[26:29], v[170:173], v[42:45]
	v_mfma_f32_16x16x32_bf16 v[6:9], v[138:141], v[170:173], v[6:9]
	v_mfma_f32_16x16x32_bf16 v[94:97], v[26:29], v[178:181], v[94:97]
	v_mfma_f32_16x16x32_bf16 v[46:49], v[138:141], v[178:181], v[46:49]
	v_mfma_f32_16x16x32_bf16 v[26:29], v[26:29], v[206:209], v[114:117]
	v_mfma_f32_16x16x32_bf16 v[34:37], v[146:149], v[162:165], v[34:37]
	v_mfma_f32_16x16x32_bf16 v[18:21], v[154:157], v[162:165], v[18:21]
	v_mfma_f32_16x16x32_bf16 v[38:41], v[146:149], v[170:173], v[38:41]
	v_mfma_f32_16x16x32_bf16 v[2:5], v[154:157], v[170:173], v[2:5]
	v_mfma_f32_16x16x32_bf16 v[90:93], v[146:149], v[178:181], v[90:93]
	v_mfma_f32_16x16x32_bf16 v[50:53], v[154:157], v[178:181], v[50:53]
	v_mfma_f32_16x16x32_bf16 v[106:109], v[146:149], v[206:209], v[106:109]
	v_mfma_f32_16x16x32_bf16 v[22:25], v[154:157], v[206:209], v[22:25]
	v_mfma_f32_16x16x32_bf16 v[118:121], v[62:65], v[166:169], v[118:121]
	v_mfma_f32_16x16x32_bf16 v[30:33], v[142:145], v[166:169], v[30:33]
	v_mfma_f32_16x16x32_bf16 v[42:45], v[62:65], v[174:177], v[42:45]
	v_mfma_f32_16x16x32_bf16 v[6:9], v[142:145], v[174:177], v[6:9]
	v_mfma_f32_16x16x32_bf16 v[94:97], v[62:65], v[182:185], v[94:97]
	v_mfma_f32_16x16x32_bf16 v[46:49], v[142:145], v[182:185], v[46:49]
	v_mfma_f32_16x16x32_bf16 v[26:29], v[62:65], v[210:213], v[26:29]
	v_mfma_f32_16x16x32_bf16 v[62:65], v[138:141], v[206:209], v[110:113]
	v_mfma_f32_16x16x32_bf16 v[34:37], v[150:153], v[166:169], v[34:37]
	v_mfma_f32_16x16x32_bf16 v[18:21], v[158:161], v[166:169], v[18:21]
	v_mfma_f32_16x16x32_bf16 v[38:41], v[150:153], v[174:177], v[38:41]
	v_mfma_f32_16x16x32_bf16 v[2:5], v[158:161], v[174:177], v[2:5]
	v_mfma_f32_16x16x32_bf16 v[90:93], v[150:153], v[182:185], v[90:93]
	v_mfma_f32_16x16x32_bf16 v[50:53], v[158:161], v[182:185], v[50:53]
	v_mfma_f32_16x16x32_bf16 v[106:109], v[150:153], v[210:213], v[106:109]
	v_mfma_f32_16x16x32_bf16 v[22:25], v[158:161], v[210:213], v[22:25]
	v_mfma_f32_16x16x32_bf16 v[62:65], v[142:145], v[210:213], v[62:65]
	s_barrier
; #define PG8_STAGE(bufoff, gbase, voff) do { _Pragma("unroll") for (int _i = 0; _i < 2; ++_i) { \
;         const unsigned m0v_ = (unsigned)(uintptr_t)(lds + (bufoff) + ldsw + _i * 8192); \
;         asm volatile("s_mov_b32 m0, %0\n\ts_nop 0\n\tglobal_load_lds_dwordx4 %1, %2\n\ts_nop 1" :: "s"(m0v_), "v"((voff)[_i]), "s"((const char*)(gbase)) : "m0", "memory"); } } while (0)
; #define PG8_LDA(dst, b, h) do { _Pragma("unroll") for (int m = 0; m < 4; ++m) _Pragma("unroll") for (int k = 0; k < 2; ++k) dst[m][k] = *(const LAS bf16x8*)(lds + PG8_SA(b, h) + aoff + m * 2048 + k * 1024); } while (0)
; #define PG8_LDB(dst, b, h) do { _Pragma("unroll") for (int n = 0; n < 2; ++n) _Pragma("unroll") for (int k = 0; k < 2; ++k) dst[n][k] = *(const LAS bf16x8*)(lds + PG8_SB(b, h) + boff + n * 2048 + k * 1024); } while (0)
; #define PG8_MMA(ai, bj, At, Bt) do { _Pragma("unroll") for (int m = 0; m < 4; ++m) _Pragma("unroll") for (int n = 0; n < 2; ++n) _Pragma("unroll") for (int k = 0; k < 2; ++k) \
;         acc[ai][bj][m][n] = __builtin_amdgcn_mfma_f32_16x16x32_bf16(Bt[n][k], At[m][k], acc[ai][bj][m][n], 0, 0, 0); } while (0)
; #define PG8_WAIT_V(n) asm volatile("s_waitcnt vmcnt(" #n ")" ::: "memory")
; #define PG8_WAIT_L(n) asm volatile("s_waitcnt lgkmcnt(" #n ")" ::: "memory")
; #define PG8_BAR __builtin_amdgcn_s_barrier()
; #define PG8_SCHED __builtin_amdgcn_sched_barrier(0)
; template <class Prob, class Epi, class Sched>
; __device__ __forceinline__ void gemm_phase(LAS unsigned char* lds, const Prob& P, const Sched& S, const Epi& E) {
;     ...
;             PG8_LDB(B0, 1, 0); PG8_LDB(B1, 1, 1); PG8_SCHED; PG8_LDA(At, 1, 0); PG8_STAGE(PG8_SA(0, 1), a2 + hstepA, voffA);
;             PG8_WAIT_V(8); PG8_WAIT_L(0); PG8_BAR; __builtin_amdgcn_s_setprio(1); PG8_MMA(0, 0, At, B0); PG8_MMA(0, 1, At, B1); __builtin_amdgcn_s_setprio(0); PG8_BAR; PG8_SCHED;
;             PG8_LDA(At, 1, 1); PG8_STAGE(PG8_SB(1, 0), b3, voffB); PG8_STAGE(PG8_SB(1, 1), b3 + hstepB, voffB); PG8_STAGE(PG8_SA(1, 0), a3, voffA);
;             PG8_WAIT_V(8); PG8_WAIT_L(0); PG8_BAR; __builtin_amdgcn_s_setprio(1); PG8_MMA(1, 0, At, B0); PG8_MMA(1, 1, At, B1); __builtin_amdgcn_s_setprio(0); PG8_BAR; PG8_SCHED;
;         }
	s_setprio 0
	ds_read_b128 v[110:113], v202
	ds_read_b128 v[114:117], v202 offset:1024
	ds_read_b128 v[138:141], v202 offset:2048
	ds_read_b128 v[142:145], v202 offset:3072
	ds_read_b128 v[146:149], v203
	ds_read_b128 v[150:153], v203 offset:1024
	ds_read_b128 v[154:157], v203 offset:2048
	ds_read_b128 v[158:161], v203 offset:3072
	ds_read_b128 v[162:165], v201 offset:32768
	ds_read_b128 v[166:169], v201 offset:33792
	ds_read_b128 v[170:173], v201 offset:34816
	ds_read_b128 v[174:177], v201 offset:35840
	ds_read_b128 v[178:181], v201 offset:36864
	ds_read_b128 v[182:185], v201 offset:37888
	ds_read_b128 v[206:209], v201 offset:38912
	ds_read_b128 v[210:213], v201 offset:39936
	s_mov_b32 m0, s35
	s_nop 0
	global_load_lds_dwordx4 v1, s[54:55]
	s_nop 1
	s_nop 0
	s_mov_b32 m0, s67
	s_nop 0
	global_load_lds_dwordx4 v197, s[54:55]
	s_nop 1
	s_add_u32 s54, s54, 0x80000
	s_addc_u32 s55, s55, 0
	s_mov_b32 m0, s68
	s_nop 0
	global_load_lds_dwordx4 v1, s[54:55]
	s_nop 1
	s_nop 0
	s_mov_b32 m0, s69
	s_nop 0
	global_load_lds_dwordx4 v197, s[54:55]
	s_nop 1
	s_waitcnt vmcnt(8)
	s_waitcnt lgkmcnt(0)
	s_setprio 1
	s_barrier
	v_mfma_f32_16x16x32_bf16 v[134:137], v[110:113], v[162:165], v[134:137]
	v_mfma_f32_16x16x32_bf16 v[70:73], v[138:141], v[162:165], v[70:73]
	v_mfma_f32_16x16x32_bf16 v[102:105], v[110:113], v[170:173], v[102:105]
	v_mfma_f32_16x16x32_bf16 v[82:85], v[138:141], v[170:173], v[82:85]
	v_mfma_f32_16x16x32_bf16 v[78:81], v[110:113], v[178:181], v[78:81]
	v_mfma_f32_16x16x32_bf16 v[14:17], v[138:141], v[178:181], v[14:17]
	v_mfma_f32_16x16x32_bf16 v[130:133], v[110:113], v[206:209], v[130:133]
	v_mfma_f32_16x16x32_bf16 v[126:129], v[138:141], v[206:209], v[126:129]
	v_mfma_f32_16x16x32_bf16 v[66:69], v[146:149], v[162:165], v[66:69]
	v_mfma_f32_16x16x32_bf16 v[54:57], v[154:157], v[162:165], v[54:57]
	v_mfma_f32_16x16x32_bf16 v[98:101], v[146:149], v[170:173], v[98:101]
	v_mfma_f32_16x16x32_bf16 v[86:89], v[154:157], v[170:173], v[86:89]
	v_mfma_f32_16x16x32_bf16 v[74:77], v[146:149], v[178:181], v[74:77]
	v_mfma_f32_16x16x32_bf16 v[10:13], v[154:157], v[178:181], v[10:13]
	v_mfma_f32_16x16x32_bf16 v[122:125], v[146:149], v[206:209], v[122:125]
	v_mfma_f32_16x16x32_bf16 v[58:61], v[154:157], v[206:209], v[58:61]
	v_mfma_f32_16x16x32_bf16 v[134:137], v[114:117], v[166:169], v[134:137]
	v_mfma_f32_16x16x32_bf16 v[70:73], v[142:145], v[166:169], v[70:73]
	v_mfma_f32_16x16x32_bf16 v[102:105], v[114:117], v[174:177], v[102:105]
	v_mfma_f32_16x16x32_bf16 v[82:85], v[142:145], v[174:177], v[82:85]
	v_mfma_f32_16x16x32_bf16 v[78:81], v[114:117], v[182:185], v[78:81]
	v_mfma_f32_16x16x32_bf16 v[14:17], v[142:145], v[182:185], v[14:17]
	v_mfma_f32_16x16x32_bf16 v[130:133], v[114:117], v[210:213], v[130:133]
	v_mfma_f32_16x16x32_bf16 v[126:129], v[142:145], v[210:213], v[126:129]
	v_mfma_f32_16x16x32_bf16 v[66:69], v[150:153], v[166:169], v[66:69]
	v_mfma_f32_16x16x32_bf16 v[54:57], v[158:161], v[166:169], v[54:57]
	v_mfma_f32_16x16x32_bf16 v[98:101], v[150:153], v[174:177], v[98:101]
	v_mfma_f32_16x16x32_bf16 v[86:89], v[158:161], v[174:177], v[86:89]
	v_mfma_f32_16x16x32_bf16 v[74:77], v[150:153], v[182:185], v[74:77]
	v_mfma_f32_16x16x32_bf16 v[10:13], v[158:161], v[182:185], v[10:13]
	v_mfma_f32_16x16x32_bf16 v[122:125], v[150:153], v[210:213], v[122:125]
	v_mfma_f32_16x16x32_bf16 v[58:61], v[158:161], v[210:213], v[58:61]
	s_barrier
	s_setprio 0
	ds_read_b128 v[162:165], v201 offset:49152
	ds_read_b128 v[166:169], v201 offset:50176
	ds_read_b128 v[170:173], v201 offset:51200
	ds_read_b128 v[174:177], v201 offset:52224
	ds_read_b128 v[178:181], v201 offset:53248
	ds_read_b128 v[182:185], v201 offset:54272
	ds_read_b128 v[206:209], v201 offset:55296
	ds_read_b128 v[210:213], v201 offset:56320
	s_add_u32 s54, s8, 0x80
	s_addc_u32 s55, s9, 0
	s_mov_b32 m0, s74
	s_nop 0
	global_load_lds_dwordx4 v196, s[54:55]
	s_nop 1
	s_add_u32 s8, s8, 0x80080
	s_mov_b32 m0, s75
	s_nop 0
	global_load_lds_dwordx4 v198, s[54:55]
	s_nop 1
	s_addc_u32 s9, s9, 0
	s_mov_b32 m0, s78
	s_nop 0
	global_load_lds_dwordx4 v196, s[8:9]
	s_nop 1
	s_nop 0
	s_mov_b32 m0, s79
	s_nop 0
	global_load_lds_dwordx4 v198, s[8:9]
	s_nop 1
	s_nop 0
	s_waitcnt vmcnt(6)
	s_waitcnt lgkmcnt(0)
	s_setprio 1
	s_barrier
	v_mfma_f32_16x16x32_bf16 v[118:121], v[110:113], v[162:165], v[118:121]
	v_mfma_f32_16x16x32_bf16 v[42:45], v[110:113], v[170:173], v[42:45]
	s_add_i32 s65, s65, 2
	v_mfma_f32_16x16x32_bf16 v[94:97], v[110:113], v[178:181], v[94:97]
	s_add_u32 s49, s49, 0x100
	v_mfma_f32_16x16x32_bf16 v[26:29], v[110:113], v[206:209], v[26:29]
	s_addc_u32 s51, s51, 0
	v_mfma_f32_16x16x32_bf16 v[118:121], v[114:117], v[166:169], v[118:121]
	s_add_u32 s63, s63, 0x100
	v_mfma_f32_16x16x32_bf16 v[42:45], v[114:117], v[174:177], v[42:45]
	s_addc_u32 s64, s64, 0
	v_mfma_f32_16x16x32_bf16 v[94:97], v[114:117], v[182:185], v[94:97]
	s_add_u32 s4, s4, 0x100
	v_mfma_f32_16x16x32_bf16 v[114:117], v[114:117], v[210:213], v[26:29]
	s_addc_u32 s5, s5, 0
	v_mfma_f32_16x16x32_bf16 v[26:29], v[138:141], v[206:209], v[62:65]
	v_mfma_f32_16x16x32_bf16 v[110:113], v[142:145], v[210:213], v[26:29]
	v_mfma_f32_16x16x32_bf16 v[26:29], v[146:149], v[162:165], v[34:37]
	v_mfma_f32_16x16x32_bf16 v[34:37], v[150:153], v[166:169], v[26:29]
	v_mfma_f32_16x16x32_bf16 v[26:29], v[146:149], v[170:173], v[38:41]
	v_mfma_f32_16x16x32_bf16 v[38:41], v[150:153], v[174:177], v[26:29]
	v_mfma_f32_16x16x32_bf16 v[26:29], v[146:149], v[178:181], v[90:93]
	v_mfma_f32_16x16x32_bf16 v[90:93], v[150:153], v[182:185], v[26:29]
	v_mfma_f32_16x16x32_bf16 v[26:29], v[154:157], v[178:181], v[50:53]
	v_mfma_f32_16x16x32_bf16 v[30:33], v[138:141], v[162:165], v[30:33]
	v_mfma_f32_16x16x32_bf16 v[6:9], v[138:141], v[170:173], v[6:9]
	v_mfma_f32_16x16x32_bf16 v[46:49], v[138:141], v[178:181], v[46:49]
	v_mfma_f32_16x16x32_bf16 v[18:21], v[154:157], v[162:165], v[18:21]
	v_mfma_f32_16x16x32_bf16 v[2:5], v[154:157], v[170:173], v[2:5]
	v_mfma_f32_16x16x32_bf16 v[50:53], v[158:161], v[182:185], v[26:29]
	v_mfma_f32_16x16x32_bf16 v[26:29], v[146:149], v[206:209], v[106:109]
	v_mfma_f32_16x16x32_bf16 v[22:25], v[154:157], v[206:209], v[22:25]
	v_mfma_f32_16x16x32_bf16 v[30:33], v[142:145], v[166:169], v[30:33]
	v_mfma_f32_16x16x32_bf16 v[6:9], v[142:145], v[174:177], v[6:9]
	v_mfma_f32_16x16x32_bf16 v[46:49], v[142:145], v[182:185], v[46:49]
	v_mfma_f32_16x16x32_bf16 v[18:21], v[158:161], v[166:169], v[18:21]
	v_mfma_f32_16x16x32_bf16 v[2:5], v[158:161], v[174:177], v[2:5]
	v_mfma_f32_16x16x32_bf16 v[106:109], v[150:153], v[210:213], v[26:29]
	v_mfma_f32_16x16x32_bf16 v[22:25], v[158:161], v[210:213], v[22:25]
	s_barrier
	s_setprio 0
	s_cmp_gt_u32 s65, 29
	s_cbranch_scc0 .LBB0_963
	s_and_b64 vcc, exec, s[36:37]
	s_cbranch_vccz .LBB0_966
	s_barrier

; #define PG8_STAGE(bufoff, gbase, voff) do { _Pragma("unroll") for (int _i = 0; _i < 2; ++_i) { \
;         const unsigned m0v_ = (unsigned)(uintptr_t)(lds + (bufoff) + ldsw + _i * 8192); \
;         asm volatile("s_mov_b32 m0, %0\n\ts_nop 0\n\tglobal_load_lds_dwordx4 %1, %2\n\ts_nop 1" :: "s"(m0v_), "v"((voff)[_i]), "s"((const char*)(gbase)) : "m0", "memory"); } } while (0)
; #define PG8_LDA(dst, b, h) do { _Pragma("unroll") for (int m = 0; m < 4; ++m) _Pragma("unroll") for (int k = 0; k < 2; ++k) dst[m][k] = *(const LAS bf16x8*)(lds + PG8_SA(b, h) + aoff + m * 2048 + k * 1024); } while (0)
; #define PG8_LDB(dst, b, h) do { _Pragma("unroll") for (int n = 0; n < 2; ++n) _Pragma("unroll") for (int k = 0; k < 2; ++k) dst[n][k] = *(const LAS bf16x8*)(lds + PG8_SB(b, h) + boff + n * 2048 + k * 1024); } while (0)
; #define PG8_MMA(ai, bj, At, Bt) do { _Pragma("unroll") for (int m = 0; m < 4; ++m) _Pragma("unroll") for (int n = 0; n < 2; ++n) _Pragma("unroll") for (int k = 0; k < 2; ++k) \
;         acc[ai][bj][m][n] = __builtin_amdgcn_mfma_f32_16x16x32_bf16(Bt[n][k], At[m][k], acc[ai][bj][m][n], 0, 0, 0); } while (0)
; #define PG8_WAIT_V(n) asm volatile("s_waitcnt vmcnt(" #n ")" ::: "memory")
; #define PG8_WAIT_L(n) asm volatile("s_waitcnt lgkmcnt(" #n ")" ::: "memory")
; #define PG8_BAR __builtin_amdgcn_s_barrier()
; #define PG8_SCHED __builtin_amdgcn_sched_barrier(0)
; template <class Prob, class Epi, class Sched>
; __device__ __forceinline__ void gemm_phase(LAS unsigned char* lds, const Prob& P, const Sched& S, const Epi& E) {
;     ...
;             const char* a1 = cA + (size_t)(t + 1) * kstep;
;             const char* a2 = last ? nA : cA + (size_t)(t + 2) * kstep; const char* b2 = last ? nB : cB + (size_t)(t + 2) * kstep;
;             const char* a3 = a2 + kstep; const char* b3 = b2 + kstep;
;             PG8_LDB(B0, 0, 0); PG8_LDB(B1, 0, 1); PG8_SCHED; PG8_LDA(At, 0, 0); PG8_STAGE(PG8_SA(1, 1), a1 + hstepA, voffA);
;             PG8_WAIT_V(8); PG8_WAIT_L(0); PG8_BAR; __builtin_amdgcn_s_setprio(1); PG8_MMA(0, 0, At, B0); PG8_MMA(0, 1, At, B1); __builtin_amdgcn_s_setprio(0); PG8_BAR; PG8_SCHED;
.LBB0_1159:
	v_add_u32_e32 v142, 0x10000, v168
	v_add_u32_e32 v146, 0x14000, v168
	ds_read_b128 v[130:133], v142
	ds_read_b128 v[134:137], v142 offset:1024
	ds_read_b128 v[138:141], v142 offset:2048
	ds_read_b128 v[142:145], v142 offset:3072
	ds_read_b128 v[148:151], v146
	ds_read_b128 v[164:167], v146 offset:1024
	ds_read_b128 v[174:177], v146 offset:2048
	ds_read_b128 v[178:181], v146 offset:3072
	ds_read_b128 v[182:185], v169
	ds_read_b128 v[186:189], v169 offset:1024
	ds_read_b128 v[190:193], v169 offset:2048
	ds_read_b128 v[194:197], v169 offset:3072
	ds_read_b128 v[198:201], v169 offset:4096
	ds_read_b128 v[202:205], v169 offset:5120
	ds_read_b128 v[206:209], v169 offset:6144
	ds_read_b128 v[210:213], v169 offset:7168
	s_add_u32 s39, s10, s4
	s_addc_u32 s45, s31, s5
	s_add_u32 s44, s39, 0xffffff80
	s_addc_u32 s45, s45, -1
	s_sub_u32 s98, s44, 0x160000
	s_subb_u32 s99, s45, 0
	s_mov_b32 m0, s63
	s_nop 0
	global_load_lds_dwordx4 v155, s[98:99]
	s_nop 1
	s_nop 0
	s_mov_b32 m0, s64
	s_nop 0
	global_load_lds_dwordx4 v161, s[98:99]
	s_nop 1
	s_mov_b32 m0, s67
	s_nop 0
	global_load_lds_dwordx4 v155, s[44:45]
	s_nop 1
	s_nop 0
	s_mov_b32 m0, s70
	s_nop 0
	global_load_lds_dwordx4 v161, s[44:45]
	s_nop 1
	s_waitcnt vmcnt(8)
	s_waitcnt lgkmcnt(0)
	s_setprio 1
	s_barrier
	v_mfma_f32_16x16x32_bf16 v[2:5], v[130:133], v[182:185], v[2:5]
	v_mfma_f32_16x16x32_bf16 v[18:21], v[138:141], v[182:185], v[18:21]
	s_add_u32 s6, s2, s4
	v_mfma_f32_16x16x32_bf16 v[26:29], v[130:133], v[190:193], v[26:29]
	s_addc_u32 s7, s3, s5
	v_mfma_f32_16x16x32_bf16 v[38:41], v[138:141], v[190:193], v[38:41]
	s_cmpk_eq_i32 s37, 0x54
	v_mfma_f32_16x16x32_bf16 v[6:9], v[130:133], v[198:201], v[6:9]
	s_cselect_b32 s42, s34, s6
	v_mfma_f32_16x16x32_bf16 v[14:17], v[138:141], v[198:201], v[14:17]
	s_cselect_b32 s43, s35, s7
	v_mfma_f32_16x16x32_bf16 v[10:13], v[130:133], v[206:209], v[10:13]
	s_cselect_b32 s100, 0, s4
	v_mfma_f32_16x16x32_bf16 v[22:25], v[138:141], v[206:209], v[22:25]
	s_cselect_b32 s41, 0, s5
	v_mfma_f32_16x16x32_bf16 v[62:65], v[148:151], v[182:185], v[62:65]
	s_add_u32 s6, s42, 0x80
	v_mfma_f32_16x16x32_bf16 v[94:97], v[174:177], v[182:185], v[94:97]
	s_addc_u32 s7, s43, 0
	v_mfma_f32_16x16x32_bf16 v[30:33], v[148:151], v[190:193], v[30:33]
	s_add_u32 s40, s16, s100
	v_mfma_f32_16x16x32_bf16 v[46:49], v[174:177], v[190:193], v[46:49]
	s_addc_u32 s41, s17, s41
	v_mfma_f32_16x16x32_bf16 v[34:37], v[148:151], v[198:201], v[34:37]
	v_mfma_f32_16x16x32_bf16 v[54:57], v[174:177], v[198:201], v[54:57]
	v_mfma_f32_16x16x32_bf16 v[42:45], v[148:151], v[206:209], v[42:45]
	v_mfma_f32_16x16x32_bf16 v[58:61], v[174:177], v[206:209], v[58:61]
	v_mfma_f32_16x16x32_bf16 v[2:5], v[134:137], v[186:189], v[2:5]
	v_mfma_f32_16x16x32_bf16 v[18:21], v[142:145], v[186:189], v[18:21]
	v_mfma_f32_16x16x32_bf16 v[26:29], v[134:137], v[194:197], v[26:29]
	v_mfma_f32_16x16x32_bf16 v[38:41], v[142:145], v[194:197], v[38:41]
	v_mfma_f32_16x16x32_bf16 v[6:9], v[134:137], v[202:205], v[6:9]
	v_mfma_f32_16x16x32_bf16 v[14:17], v[142:145], v[202:205], v[14:17]
	v_mfma_f32_16x16x32_bf16 v[10:13], v[134:137], v[210:213], v[10:13]
	v_mfma_f32_16x16x32_bf16 v[22:25], v[142:145], v[210:213], v[22:25]
	v_mfma_f32_16x16x32_bf16 v[62:65], v[164:167], v[186:189], v[62:65]
	v_mfma_f32_16x16x32_bf16 v[94:97], v[178:181], v[186:189], v[94:97]
	v_mfma_f32_16x16x32_bf16 v[30:33], v[164:167], v[194:197], v[30:33]
	v_mfma_f32_16x16x32_bf16 v[46:49], v[178:181], v[194:197], v[46:49]
	v_mfma_f32_16x16x32_bf16 v[34:37], v[164:167], v[202:205], v[34:37]
	v_mfma_f32_16x16x32_bf16 v[54:57], v[178:181], v[202:205], v[54:57]
	v_mfma_f32_16x16x32_bf16 v[42:45], v[164:167], v[210:213], v[42:45]
	v_mfma_f32_16x16x32_bf16 v[58:61], v[178:181], v[210:213], v[58:61]
	s_barrier
	s_setprio 0
	ds_read_b128 v[182:185], v169 offset:16384
	ds_read_b128 v[186:189], v169 offset:17408
	ds_read_b128 v[190:193], v169 offset:18432
	ds_read_b128 v[194:197], v169 offset:19456
	ds_read_b128 v[198:201], v169 offset:20480
	ds_read_b128 v[202:205], v169 offset:21504
	ds_read_b128 v[206:209], v169 offset:22528
	ds_read_b128 v[210:213], v169 offset:23552
	s_mov_b32 m0, s50
	s_nop 0
	global_load_lds_dwordx4 v159, s[40:41]
	s_nop 1
	s_add_u32 s44, s40, 0x160000
	s_mov_b32 m0, s51
	s_nop 0
	global_load_lds_dwordx4 v163, s[40:41]
	s_nop 1
	s_addc_u32 s45, s41, 0
	s_mov_b32 m0, s52
	s_nop 0
	global_load_lds_dwordx4 v159, s[44:45]
	s_nop 1
	s_nop 0
	s_mov_b32 m0, s53
	s_nop 0
	global_load_lds_dwordx4 v163, s[44:45]
	s_nop 1
	s_nop 0
	s_waitcnt vmcnt(6)
	s_waitcnt lgkmcnt(0)
	s_setprio 1
	s_barrier
; #define PG8_STAGE(bufoff, gbase, voff) do { _Pragma("unroll") for (int _i = 0; _i < 2; ++_i) { \
;         const unsigned m0v_ = (unsigned)(uintptr_t)(lds + (bufoff) + ldsw + _i * 8192); \
;         asm volatile("s_mov_b32 m0, %0\n\ts_nop 0\n\tglobal_load_lds_dwordx4 %1, %2\n\ts_nop 1" :: "s"(m0v_), "v"((voff)[_i]), "s"((const char*)(gbase)) : "m0", "memory"); } } while (0)
; #define PG8_LDA(dst, b, h) do { _Pragma("unroll") for (int m = 0; m < 4; ++m) _Pragma("unroll") for (int k = 0; k < 2; ++k) dst[m][k] = *(const LAS bf16x8*)(lds + PG8_SA(b, h) + aoff + m * 2048 + k * 1024); } while (0)
; #define PG8_LDB(dst, b, h) do { _Pragma("unroll") for (int n = 0; n < 2; ++n) _Pragma("unroll") for (int k = 0; k < 2; ++k) dst[n][k] = *(const LAS bf16x8*)(lds + PG8_SB(b, h) + boff + n * 2048 + k * 1024); } while (0)
; #define PG8_MMA(ai, bj, At, Bt) do { _Pragma("unroll") for (int m = 0; m < 4; ++m) _Pragma("unroll") for (int n = 0; n < 2; ++n) _Pragma("unroll") for (int k = 0; k < 2; ++k) \
;         acc[ai][bj][m][n] = __builtin_amdgcn_mfma_f32_16x16x32_bf16(Bt[n][k], At[m][k], acc[ai][bj][m][n], 0, 0, 0); } while (0)
; #define PG8_WAIT_V(n) asm volatile("s_waitcnt vmcnt(" #n ")" ::: "memory")
; #define PG8_WAIT_L(n) asm volatile("s_waitcnt lgkmcnt(" #n ")" ::: "memory")
; #define PG8_BAR __builtin_amdgcn_s_barrier()
; #define PG8_SCHED __builtin_amdgcn_sched_barrier(0)
; template <class Prob, class Epi, class Sched>
; __device__ __forceinline__ void gemm_phase(LAS unsigned char* lds, const Prob& P, const Sched& S, const Epi& E) {
;     ...
;             PG8_LDA(At, 0, 1); PG8_STAGE(PG8_SB(0, 0), b2, voffB); PG8_STAGE(PG8_SB(0, 1), b2 + hstepB, voffB); PG8_STAGE(PG8_SA(0, 0), a2, voffA);
;             PG8_WAIT_V(8); PG8_WAIT_L(0); PG8_BAR; __builtin_amdgcn_s_setprio(1); PG8_MMA(1, 0, At, B0); PG8_MMA(1, 1, At, B1); __builtin_amdgcn_s_setprio(0); PG8_BAR; PG8_SCHED;
;             PG8_LDB(B0, 1, 0); PG8_LDB(B1, 1, 1); PG8_SCHED; PG8_LDA(At, 1, 0); PG8_STAGE(PG8_SA(0, 1), a2 + hstepA, voffA);
	v_mfma_f32_16x16x32_bf16 v[78:81], v[130:133], v[182:185], v[78:81]
	v_mfma_f32_16x16x32_bf16 v[90:93], v[138:141], v[182:185], v[90:93]
	v_mfma_f32_16x16x32_bf16 v[74:77], v[130:133], v[190:193], v[74:77]
	v_mfma_f32_16x16x32_bf16 v[86:89], v[138:141], v[190:193], v[86:89]
	v_mfma_f32_16x16x32_bf16 v[70:73], v[130:133], v[198:201], v[70:73]
	v_mfma_f32_16x16x32_bf16 v[82:85], v[138:141], v[198:201], v[82:85]
	v_mfma_f32_16x16x32_bf16 v[66:69], v[130:133], v[206:209], v[66:69]
	v_mfma_f32_16x16x32_bf16 v[50:53], v[138:141], v[206:209], v[50:53]
	v_mfma_f32_16x16x32_bf16 v[114:117], v[148:151], v[182:185], v[114:117]
	v_mfma_f32_16x16x32_bf16 v[126:129], v[174:177], v[182:185], v[126:129]
	v_mfma_f32_16x16x32_bf16 v[110:113], v[148:151], v[190:193], v[110:113]
	v_mfma_f32_16x16x32_bf16 v[122:125], v[174:177], v[190:193], v[122:125]
	v_mfma_f32_16x16x32_bf16 v[106:109], v[148:151], v[198:201], v[106:109]
	v_mfma_f32_16x16x32_bf16 v[118:121], v[174:177], v[198:201], v[118:121]
	v_mfma_f32_16x16x32_bf16 v[102:105], v[148:151], v[206:209], v[102:105]
	v_mfma_f32_16x16x32_bf16 v[98:101], v[174:177], v[206:209], v[98:101]
	v_mfma_f32_16x16x32_bf16 v[78:81], v[134:137], v[186:189], v[78:81]
	v_mfma_f32_16x16x32_bf16 v[90:93], v[142:145], v[186:189], v[90:93]
	v_mfma_f32_16x16x32_bf16 v[74:77], v[134:137], v[194:197], v[74:77]
	v_mfma_f32_16x16x32_bf16 v[86:89], v[142:145], v[194:197], v[86:89]
	v_mfma_f32_16x16x32_bf16 v[70:73], v[134:137], v[202:205], v[70:73]
	v_mfma_f32_16x16x32_bf16 v[82:85], v[142:145], v[202:205], v[82:85]
	v_mfma_f32_16x16x32_bf16 v[66:69], v[134:137], v[210:213], v[66:69]
	v_mfma_f32_16x16x32_bf16 v[50:53], v[142:145], v[210:213], v[50:53]
	v_mfma_f32_16x16x32_bf16 v[114:117], v[164:167], v[186:189], v[114:117]
	v_mfma_f32_16x16x32_bf16 v[126:129], v[178:181], v[186:189], v[126:129]
	v_mfma_f32_16x16x32_bf16 v[110:113], v[164:167], v[194:197], v[110:113]
	v_mfma_f32_16x16x32_bf16 v[122:125], v[178:181], v[194:197], v[122:125]
	v_mfma_f32_16x16x32_bf16 v[106:109], v[164:167], v[202:205], v[106:109]
	v_mfma_f32_16x16x32_bf16 v[118:121], v[178:181], v[202:205], v[118:121]
	v_mfma_f32_16x16x32_bf16 v[102:105], v[164:167], v[210:213], v[102:105]
	v_mfma_f32_16x16x32_bf16 v[98:101], v[178:181], v[210:213], v[98:101]
	s_barrier
	s_setprio 0
	v_add_u32_e32 v142, 0x18000, v168
	v_add_u32_e32 v146, 0x1c000, v168
	ds_read_b128 v[130:133], v142
	ds_read_b128 v[134:137], v142 offset:1024
	ds_read_b128 v[138:141], v142 offset:2048
	ds_read_b128 v[142:145], v142 offset:3072
	ds_read_b128 v[148:151], v146
	ds_read_b128 v[164:167], v146 offset:1024
	ds_read_b128 v[174:177], v146 offset:2048
	ds_read_b128 v[178:181], v146 offset:3072
	ds_read_b128 v[182:185], v169 offset:32768
	ds_read_b128 v[186:189], v169 offset:33792
	ds_read_b128 v[190:193], v169 offset:34816
	ds_read_b128 v[194:197], v169 offset:35840
	ds_read_b128 v[198:201], v169 offset:36864
	ds_read_b128 v[202:205], v169 offset:37888
	ds_read_b128 v[206:209], v169 offset:38912
	ds_read_b128 v[210:213], v169 offset:39936
	s_mov_b32 m0, s9
	s_nop 0
	global_load_lds_dwordx4 v155, s[42:43]
	s_nop 1
	s_nop 0
	s_mov_b32 m0, s54
	s_nop 0
	global_load_lds_dwordx4 v161, s[42:43]
	s_nop 1
	s_add_u32 s42, s42, 0x160000
	s_addc_u32 s43, s43, 0
	s_mov_b32 m0, s55
	s_nop 0
	global_load_lds_dwordx4 v155, s[42:43]
	s_nop 1
	s_nop 0
	s_mov_b32 m0, s56
	s_nop 0
	global_load_lds_dwordx4 v161, s[42:43]
	s_nop 1
	s_waitcnt vmcnt(8)
	s_waitcnt lgkmcnt(0)
	s_setprio 1
	s_barrier
; #define PG8_STAGE(bufoff, gbase, voff) do { _Pragma("unroll") for (int _i = 0; _i < 2; ++_i) { \
;         const unsigned m0v_ = (unsigned)(uintptr_t)(lds + (bufoff) + ldsw + _i * 8192); \
;         asm volatile("s_mov_b32 m0, %0\n\ts_nop 0\n\tglobal_load_lds_dwordx4 %1, %2\n\ts_nop 1" :: "s"(m0v_), "v"((voff)[_i]), "s"((const char*)(gbase)) : "m0", "memory"); } } while (0)
; #define PG8_LDA(dst, b, h) do { _Pragma("unroll") for (int m = 0; m < 4; ++m) _Pragma("unroll") for (int k = 0; k < 2; ++k) dst[m][k] = *(const LAS bf16x8*)(lds + PG8_SA(b, h) + aoff + m * 2048 + k * 1024); } while (0)
; #define PG8_LDB(dst, b, h) do { _Pragma("unroll") for (int n = 0; n < 2; ++n) _Pragma("unroll") for (int k = 0; k < 2; ++k) dst[n][k] = *(const LAS bf16x8*)(lds + PG8_SB(b, h) + boff + n * 2048 + k * 1024); } while (0)
; #define PG8_MMA(ai, bj, At, Bt) do { _Pragma("unroll") for (int m = 0; m < 4; ++m) _Pragma("unroll") for (int n = 0; n < 2; ++n) _Pragma("unroll") for (int k = 0; k < 2; ++k) \
;         acc[ai][bj][m][n] = __builtin_amdgcn_mfma_f32_16x16x32_bf16(Bt[n][k], At[m][k], acc[ai][bj][m][n], 0, 0, 0); } while (0)
; #define PG8_WAIT_V(n) asm volatile("s_waitcnt vmcnt(" #n ")" ::: "memory")
; #define PG8_WAIT_L(n) asm volatile("s_waitcnt lgkmcnt(" #n ")" ::: "memory")
; #define PG8_BAR __builtin_amdgcn_s_barrier()
; #define PG8_SCHED __builtin_amdgcn_sched_barrier(0)
; template <class Prob, class Epi, class Sched>
; __device__ __forceinline__ void gemm_phase(LAS unsigned char* lds, const Prob& P, const Sched& S, const Epi& E) {
;     ...
;             PG8_LDB(B0, 1, 0); PG8_LDB(B1, 1, 1); PG8_SCHED; PG8_LDA(At, 1, 0); PG8_STAGE(PG8_SA(0, 1), a2 + hstepA, voffA);
;             PG8_WAIT_V(8); PG8_WAIT_L(0); PG8_BAR; __builtin_amdgcn_s_setprio(1); PG8_MMA(0, 0, At, B0); PG8_MMA(0, 1, At, B1); __builtin_amdgcn_s_setprio(0); PG8_BAR; PG8_SCHED;
;             PG8_LDA(At, 1, 1); PG8_STAGE(PG8_SB(1, 0), b3, voffB); PG8_STAGE(PG8_SB(1, 1), b3 + hstepB, voffB); PG8_STAGE(PG8_SA(1, 0), a3, voffA);
;             PG8_WAIT_V(8); PG8_WAIT_L(0); PG8_BAR; __builtin_amdgcn_s_setprio(1); PG8_MMA(1, 0, At, B0); PG8_MMA(1, 1, At, B1); __builtin_amdgcn_s_setprio(0); PG8_BAR; PG8_SCHED;
;         }
	v_mfma_f32_16x16x32_bf16 v[2:5], v[130:133], v[182:185], v[2:5]
	v_mfma_f32_16x16x32_bf16 v[18:21], v[138:141], v[182:185], v[18:21]
	v_mfma_f32_16x16x32_bf16 v[26:29], v[130:133], v[190:193], v[26:29]
	v_mfma_f32_16x16x32_bf16 v[38:41], v[138:141], v[190:193], v[38:41]
	v_mfma_f32_16x16x32_bf16 v[6:9], v[130:133], v[198:201], v[6:9]
	v_mfma_f32_16x16x32_bf16 v[14:17], v[138:141], v[198:201], v[14:17]
	v_mfma_f32_16x16x32_bf16 v[10:13], v[130:133], v[206:209], v[10:13]
	v_mfma_f32_16x16x32_bf16 v[22:25], v[138:141], v[206:209], v[22:25]
	v_mfma_f32_16x16x32_bf16 v[62:65], v[148:151], v[182:185], v[62:65]
	v_mfma_f32_16x16x32_bf16 v[94:97], v[174:177], v[182:185], v[94:97]
	v_mfma_f32_16x16x32_bf16 v[30:33], v[148:151], v[190:193], v[30:33]
	v_mfma_f32_16x16x32_bf16 v[46:49], v[174:177], v[190:193], v[46:49]
	v_mfma_f32_16x16x32_bf16 v[34:37], v[148:151], v[198:201], v[34:37]
	v_mfma_f32_16x16x32_bf16 v[54:57], v[174:177], v[198:201], v[54:57]
	v_mfma_f32_16x16x32_bf16 v[42:45], v[148:151], v[206:209], v[42:45]
	v_mfma_f32_16x16x32_bf16 v[58:61], v[174:177], v[206:209], v[58:61]
	v_mfma_f32_16x16x32_bf16 v[2:5], v[134:137], v[186:189], v[2:5]
	v_mfma_f32_16x16x32_bf16 v[18:21], v[142:145], v[186:189], v[18:21]
	v_mfma_f32_16x16x32_bf16 v[26:29], v[134:137], v[194:197], v[26:29]
	v_mfma_f32_16x16x32_bf16 v[38:41], v[142:145], v[194:197], v[38:41]
	v_mfma_f32_16x16x32_bf16 v[6:9], v[134:137], v[202:205], v[6:9]
	v_mfma_f32_16x16x32_bf16 v[14:17], v[142:145], v[202:205], v[14:17]
	v_mfma_f32_16x16x32_bf16 v[10:13], v[134:137], v[210:213], v[10:13]
	v_mfma_f32_16x16x32_bf16 v[22:25], v[142:145], v[210:213], v[22:25]
	v_mfma_f32_16x16x32_bf16 v[62:65], v[164:167], v[186:189], v[62:65]
	v_mfma_f32_16x16x32_bf16 v[94:97], v[178:181], v[186:189], v[94:97]
	v_mfma_f32_16x16x32_bf16 v[30:33], v[164:167], v[194:197], v[30:33]
	v_mfma_f32_16x16x32_bf16 v[46:49], v[178:181], v[194:197], v[46:49]
	v_mfma_f32_16x16x32_bf16 v[34:37], v[164:167], v[202:205], v[34:37]
	v_mfma_f32_16x16x32_bf16 v[54:57], v[178:181], v[202:205], v[54:57]
	v_mfma_f32_16x16x32_bf16 v[42:45], v[164:167], v[210:213], v[42:45]
	v_mfma_f32_16x16x32_bf16 v[58:61], v[178:181], v[210:213], v[58:61]
	s_barrier
	s_setprio 0
	ds_read_b128 v[182:185], v169 offset:49152
	ds_read_b128 v[186:189], v169 offset:50176
	ds_read_b128 v[190:193], v169 offset:51200
	ds_read_b128 v[194:197], v169 offset:52224
	ds_read_b128 v[198:201], v169 offset:53248
	ds_read_b128 v[202:205], v169 offset:54272
	ds_read_b128 v[206:209], v169 offset:55296
	ds_read_b128 v[210:213], v169 offset:56320
	s_add_u32 s42, s40, 0x80
	s_addc_u32 s43, s41, 0
	s_mov_b32 m0, s61
	s_nop 0
	global_load_lds_dwordx4 v159, s[42:43]
	s_nop 1
	s_add_u32 s40, s40, 0x160080
	s_mov_b32 m0, s62
	s_nop 0
	global_load_lds_dwordx4 v163, s[42:43]
	s_nop 1
	s_addc_u32 s41, s41, 0
	s_mov_b32 m0, s65
	s_nop 0
	global_load_lds_dwordx4 v159, s[40:41]
	s_nop 1
	s_nop 0
	s_mov_b32 m0, s66
	s_nop 0
	global_load_lds_dwordx4 v163, s[40:41]
	s_nop 1
	s_nop 0
	s_waitcnt vmcnt(6)
	s_waitcnt lgkmcnt(0)
	s_setprio 1
	s_barrier
	v_mfma_f32_16x16x32_bf16 v[78:81], v[130:133], v[182:185], v[78:81]
	v_mfma_f32_16x16x32_bf16 v[90:93], v[138:141], v[182:185], v[90:93]
	s_add_i32 s37, s37, 2
	v_mfma_f32_16x16x32_bf16 v[74:77], v[130:133], v[190:193], v[74:77]
	s_add_u32 s4, s4, 0x100
	v_mfma_f32_16x16x32_bf16 v[86:89], v[138:141], v[190:193], v[86:89]
	s_addc_u32 s5, s5, 0
	v_mfma_f32_16x16x32_bf16 v[70:73], v[130:133], v[198:201], v[70:73]
	v_mfma_f32_16x16x32_bf16 v[82:85], v[138:141], v[198:201], v[82:85]
	v_mfma_f32_16x16x32_bf16 v[66:69], v[130:133], v[206:209], v[66:69]
	v_mfma_f32_16x16x32_bf16 v[50:53], v[138:141], v[206:209], v[50:53]
	v_mfma_f32_16x16x32_bf16 v[114:117], v[148:151], v[182:185], v[114:117]
	v_mfma_f32_16x16x32_bf16 v[126:129], v[174:177], v[182:185], v[126:129]
	v_mfma_f32_16x16x32_bf16 v[110:113], v[148:151], v[190:193], v[110:113]
	v_mfma_f32_16x16x32_bf16 v[122:125], v[174:177], v[190:193], v[122:125]
	v_mfma_f32_16x16x32_bf16 v[106:109], v[148:151], v[198:201], v[106:109]
	v_mfma_f32_16x16x32_bf16 v[118:121], v[174:177], v[198:201], v[118:121]
	v_mfma_f32_16x16x32_bf16 v[102:105], v[148:151], v[206:209], v[102:105]
	v_mfma_f32_16x16x32_bf16 v[98:101], v[174:177], v[206:209], v[98:101]
	v_mfma_f32_16x16x32_bf16 v[78:81], v[134:137], v[186:189], v[78:81]
	v_mfma_f32_16x16x32_bf16 v[90:93], v[142:145], v[186:189], v[90:93]
	v_mfma_f32_16x16x32_bf16 v[74:77], v[134:137], v[194:197], v[74:77]
	v_mfma_f32_16x16x32_bf16 v[86:89], v[142:145], v[194:197], v[86:89]
	v_mfma_f32_16x16x32_bf16 v[70:73], v[134:137], v[202:205], v[70:73]
	v_mfma_f32_16x16x32_bf16 v[82:85], v[142:145], v[202:205], v[82:85]
	v_mfma_f32_16x16x32_bf16 v[66:69], v[134:137], v[210:213], v[66:69]
	v_mfma_f32_16x16x32_bf16 v[50:53], v[142:145], v[210:213], v[50:53]
	v_mfma_f32_16x16x32_bf16 v[114:117], v[164:167], v[186:189], v[114:117]
	v_mfma_f32_16x16x32_bf16 v[126:129], v[178:181], v[186:189], v[126:129]
	v_mfma_f32_16x16x32_bf16 v[110:113], v[164:167], v[194:197], v[110:113]
	v_mfma_f32_16x16x32_bf16 v[122:125], v[178:181], v[194:197], v[122:125]
	v_mfma_f32_16x16x32_bf16 v[106:109], v[164:167], v[202:205], v[106:109]
	v_mfma_f32_16x16x32_bf16 v[118:121], v[178:181], v[202:205], v[118:121]
	v_mfma_f32_16x16x32_bf16 v[102:105], v[164:167], v[210:213], v[102:105]
	v_mfma_f32_16x16x32_bf16 v[98:101], v[178:181], v[210:213], v[98:101]
	s_barrier
	s_setprio 0
	s_cmpk_gt_u32 s37, 0x55
	s_cbranch_scc0 .LBB0_1159
	s_and_b64 vcc, exec, s[20:21]
	s_cbranch_vccz .LBB0_1162
	s_barrier
